# v16 + tail GEMM epilogue operands (residual tile, LN stats, gamma/beta, gate tiles) prefetched inside the K-loop instead of 1-3 serialized round trips after the reduce
# baseline (speedup 1.0000x reference)
; #define LAS __attribute__((address_space(3)))
; __device__ __forceinline__ float bflo(unsigned w) { return __uint_as_float(w << 16); }
; __device__ __forceinline__ float bfhi(unsigned w) { return __uint_as_float(w & 0xffff0000u); }
; __device__ __forceinline__ u32x4 pack8(f32x4 a, f32x4 b) { u32x4 w; w.x = cvtpk(a[0], a[1]); w.y = cvtpk(a[2], a[3]); w.z = cvtpk(b[0], b[1]); w.w = cvtpk(b[2], b[3]); return w; }
; #define BAR_LDS() do { asm volatile("s_waitcnt lgkmcnt(0)" ::: "memory"); __builtin_amdgcn_s_barrier(); asm volatile("" ::: "memory"); } while (0)
; template <int EPI> __device__ __forceinline__ void tail_gemm(LAS unsigned char* lds, const bf16* Am, const bf16* Bt, int K, const TailEpi& E, int tid_in) {
;     ...
;     LAS float* part = (LAS float*)lds + (size_t)w * 64 * 65;
; #pragma unroll
;     for (int i = 0; i < 4; ++i)
; #pragma unroll
;         for (int j = 0; j < 4; ++j)
; #pragma unroll
;             for (int r = 0; r < 4; ++r) part[(16 * i + 4 * q4 + r) * 65 + 16 * j + l15] = acc[i][j][r];
;     BAR_LDS();
;     const int rl = tid >> 3, c8 = (tid & 7) * 8, row = row0 + rl, col = col0 + c8;
;     f32x4 v0 = {0.f, 0.f, 0.f, 0.f}, v1 = v0;
; #pragma unroll
;     for (int ww = 0; ww < 8; ++ww) { const LAS float* p = (const LAS float*)lds + (size_t)ww * 64 * 65 + rl * 65 + c8;
;         v0[0] += p[0]; v0[1] += p[1]; v0[2] += p[2]; v0[3] += p[3]; v1[0] += p[4]; v1[1] += p[5]; v1[2] += p[6]; v1[3] += p[7]; }
;     const size_t off = (size_t)row * 1024 + col;
;     if (EPI == 0 || EPI == 1) {
;         const u32x4 s = *(const u32x4*)(E.S + off);
;         v0[0] *= bflo(s.x); v0[1] *= bfhi(s.x); v0[2] *= bflo(s.y); v0[3] *= bfhi(s.y); v1[0] *= bflo(s.z); v1[1] *= bfhi(s.z); v1[2] *= bflo(s.w); v1[3] *= bfhi(s.w);
;         if (EPI == 1) { const u32x4 a = *(const u32x4*)(E.A + off);
;             v0[0] += bflo(a.x); v0[1] += bfhi(a.x); v0[2] += bflo(a.y); v0[3] += bfhi(a.y); v1[0] += bflo(a.z); v1[1] += bfhi(a.z); v1[2] += bflo(a.w); v1[3] += bfhi(a.w); }
;         *(u32x4*)(E.S + off) = pack8(v0, v1);
.LBB0_1315:
	s_or_b64 exec, exec, s[2:3]
	ds_write2_b32 v181, v60, v56 offset1:16
	ds_write2_b32 v181, v61, v57 offset0:65 offset1:81
	ds_write2_b32 v181, v62, v58 offset0:130 offset1:146
	ds_write2_b32 v181, v63, v59 offset0:195 offset1:211
	ds_write2_b32 v181, v44, v40 offset0:32 offset1:48
	ds_write2_b32 v181, v45, v41 offset0:97 offset1:113
	ds_write2_b32 v181, v46, v42 offset0:162 offset1:178
	ds_write2_b32 v181, v47, v43 offset0:227 offset1:243
	v_add_u32_e32 v40, 0x1000, v181
	ds_write2_b32 v40, v28, v24 offset0:16 offset1:32
	ds_write2_b32 v40, v29, v25 offset0:81 offset1:97
	ds_write2_b32 v40, v30, v26 offset0:146 offset1:162
	ds_write2_b32 v40, v31, v27 offset0:211 offset1:227
	ds_write2_b32 v40, v12, v8 offset0:48 offset1:64
	ds_write2_b32 v40, v13, v9 offset0:113 offset1:129
	ds_write2_b32 v40, v14, v10 offset0:178 offset1:194
	v_add_u32_e32 v8, 0x1200, v181
	ds_write2_b32 v8, v15, v11 offset0:115 offset1:131
	v_add_u32_e32 v8, 0x2000, v181
	ds_write2_b32 v8, v48, v52 offset0:32 offset1:48
	ds_write2_b32 v8, v49, v53 offset0:97 offset1:113
	ds_write2_b32 v8, v50, v54 offset0:162 offset1:178
	ds_write2_b32 v8, v51, v55 offset0:227 offset1:243
	ds_write2_b32 v8, v32, v36 offset0:64 offset1:80
	ds_write2_b32 v8, v33, v37 offset0:129 offset1:145
	ds_write2_b32 v8, v34, v38 offset0:194 offset1:210
	v_add_u32_e32 v8, 0x2400, v181
	ds_write2_b32 v8, v35, v39 offset0:3 offset1:19
	v_add_u32_e32 v8, 0x3000, v181
	v_add_u32_e32 v9, 0x3200, v181
	ds_write2_b32 v8, v16, v20 offset0:48 offset1:64
	ds_write2_b32 v8, v17, v21 offset0:113 offset1:129
	ds_write2_b32 v8, v18, v22 offset0:178 offset1:194
	ds_write2_b32 v9, v19, v23 offset0:115 offset1:131
	ds_write2_b32 v8, v0, v4 offset0:80 offset1:96
	ds_write2_b32 v8, v1, v5 offset0:145 offset1:161
	ds_write2_b32 v8, v2, v6 offset0:210 offset1:226
	v_add_u32_e32 v0, 0x3400, v181
	ds_write2_b32 v0, v3, v7 offset0:19 offset1:35
	v_add_u32_e32 v0, s1, v178
	v_ashrrev_i32_e32 v1, 31, v0
	v_or_b32_e32 v2, s12, v179
	v_lshlrev_b64 v[0:1], 11, v[0:1]
	v_lshl_add_u64 v[0:1], s[80:81], 0, v[0:1]
	v_lshlrev_b32_e32 v80, 1, v2
	s_waitcnt lgkmcnt(0)
	s_barrier
	v_lshl_add_u64 v[4:5], v[0:1], 0, v[80:81]
	s_waitcnt vmcnt(0)
	v_mov_b32_e32 v0, v132
	v_mov_b32_e32 v1, v133
	v_mov_b32_e32 v2, v134
	v_mov_b32_e32 v3, v135
	v_add_u32_e32 v14, 0x4100, v180
	v_add_u32_e32 v16, 0x8200, v180
	v_add_u32_e32 v18, 0xc300, v180
	ds_read2_b32 v[6:7], v180 offset1:1
	ds_read2_b32 v[8:9], v180 offset0:2 offset1:3
	ds_read2_b32 v[10:11], v180 offset0:4 offset1:5
	ds_read2_b32 v[12:13], v180 offset0:6 offset1:7
	ds_read2_b32 v[14:15], v14 offset1:1
	ds_read2_b32 v[16:17], v16 offset1:1
	ds_read2_b32 v[18:19], v18 offset1:1
	s_waitcnt lgkmcnt(6)
	v_pk_add_f32 v[6:7], v[6:7], 0 op_sel_hi:[1,0]
	v_add_u32_e32 v20, 0x4108, v180
	s_waitcnt lgkmcnt(2)
	v_pk_add_f32 v[6:7], v[6:7], v[14:15]
	ds_read2_b32 v[20:21], v20 offset1:1
	s_waitcnt lgkmcnt(2)
	v_pk_add_f32 v[6:7], v[6:7], v[16:17]
	v_pk_add_f32 v[8:9], v[8:9], 0 op_sel_hi:[1,0]
	s_waitcnt lgkmcnt(1)
	v_pk_add_f32 v[6:7], v[6:7], v[18:19]
	ds_read2_b32 v[14:15], v182 offset1:1
	ds_read2_b32 v[16:17], v190 offset1:1
	ds_read2_b32 v[18:19], v183 offset1:1
	ds_read2_b32 v[22:23], v184 offset1:1
	ds_read2_b32 v[24:25], v185 offset1:1
	s_waitcnt lgkmcnt(4)
	v_pk_add_f32 v[6:7], v[6:7], v[14:15]
	ds_read2_b32 v[14:15], v191 offset1:1
	ds_read2_b32 v[26:27], v192 offset1:1
	ds_read2_b32 v[28:29], v193 offset1:1
	s_waitcnt lgkmcnt(6)
	v_pk_add_f32 v[6:7], v[6:7], v[16:17]
	ds_read2_b32 v[16:17], v194 offset1:1
	ds_read2_b32 v[30:31], v198 offset1:1
	ds_read2_b32 v[32:33], v195 offset1:1
	ds_read2_b32 v[34:35], v196 offset1:1
	ds_read2_b32 v[36:37], v197 offset1:1
	s_waitcnt lgkmcnt(4)
	v_pk_add_f32 v[6:7], v[6:7], v[16:17]
	ds_read2_b32 v[16:17], v199 offset1:1
	ds_read2_b32 v[38:39], v200 offset1:1
	ds_read2_b32 v[40:41], v201 offset1:1
	s_waitcnt lgkmcnt(6)
	v_pk_add_f32 v[6:7], v[6:7], v[30:31]
	v_pk_add_f32 v[8:9], v[8:9], v[20:21]
	v_add_u32_e32 v44, 0x8210, v180
	s_add_i32 s0, s0, s30
	s_cmpk_gt_i32 s0, 0x9f
	s_waitcnt vmcnt(0)
	v_lshlrev_b32_e32 v30, 16, v0
	v_and_b32_e32 v31, 0xffff0000, v0
	v_pk_mul_f32 v[6:7], v[6:7], v[30:31]
	v_add_u32_e32 v0, 0x8208, v180
	v_add_u32_e32 v30, 0xc308, v180
	ds_read2_b32 v[20:21], v0 offset1:1
	ds_read2_b32 v[30:31], v30 offset1:1
	v_add_u32_e32 v0, 0x4110, v180
	ds_read2_b32 v[42:43], v0 offset1:1
	ds_read2_b32 v[44:45], v44 offset1:1
	v_lshlrev_b32_e32 v0, 16, v1
	s_waitcnt lgkmcnt(3)
	v_pk_add_f32 v[8:9], v[8:9], v[20:21]
	v_and_b32_e32 v1, 0xffff0000, v1
	s_waitcnt lgkmcnt(2)
	v_pk_add_f32 v[8:9], v[8:9], v[30:31]
	s_nop 0
	v_pk_add_f32 v[8:9], v[8:9], v[18:19]
	v_add_u32_e32 v18, 0xc318, v180
	v_pk_add_f32 v[8:9], v[8:9], v[14:15]
	v_add_u32_e32 v14, 0x4118, v180
	v_pk_add_f32 v[8:9], v[8:9], v[32:33]
	s_nop 0
	v_pk_add_f32 v[8:9], v[8:9], v[16:17]
	v_add_u32_e32 v16, 0x8218, v180
	v_pk_mul_f32 v[8:9], v[8:9], v[0:1]
	v_pk_add_f32 v[0:1], v[10:11], 0 op_sel_hi:[1,0]
	v_add_u32_e32 v10, 0xc310, v180
	ds_read2_b32 v[10:11], v10 offset1:1
	s_waitcnt lgkmcnt(2)
	v_pk_add_f32 v[0:1], v[0:1], v[42:43]
	ds_read2_b32 v[14:15], v14 offset1:1
	ds_read2_b32 v[16:17], v16 offset1:1
	ds_read2_b32 v[18:19], v18 offset1:1
	s_waitcnt lgkmcnt(4)
	v_pk_add_f32 v[0:1], v[0:1], v[44:45]
	s_waitcnt lgkmcnt(3)
	v_pk_add_f32 v[0:1], v[0:1], v[10:11]
	v_lshlrev_b32_e32 v10, 16, v2
	v_pk_add_f32 v[0:1], v[0:1], v[22:23]
	v_and_b32_e32 v11, 0xffff0000, v2
	v_pk_add_f32 v[0:1], v[0:1], v[26:27]
	v_lshlrev_b32_e32 v2, 16, v3
	v_pk_add_f32 v[0:1], v[0:1], v[34:35]
	v_and_b32_e32 v3, 0xffff0000, v3
	v_pk_add_f32 v[0:1], v[0:1], v[38:39]
	s_nop 0
	v_pk_mul_f32 v[10:11], v[0:1], v[10:11]
	v_pk_add_f32 v[0:1], v[12:13], 0 op_sel_hi:[1,0]
	s_waitcnt lgkmcnt(2)
	v_pk_add_f32 v[0:1], v[0:1], v[14:15]
	s_waitcnt lgkmcnt(1)
	v_pk_add_f32 v[0:1], v[0:1], v[16:17]
	s_waitcnt lgkmcnt(0)
	v_pk_add_f32 v[0:1], v[0:1], v[18:19]
	s_nop 0
	v_pk_add_f32 v[0:1], v[0:1], v[24:25]
	s_nop 0
	v_pk_add_f32 v[0:1], v[0:1], v[28:29]
	s_nop 0
	v_pk_add_f32 v[0:1], v[0:1], v[36:37]
	s_nop 0
	v_pk_add_f32 v[0:1], v[0:1], v[40:41]
	s_nop 0
	v_pk_mul_f32 v[12:13], v[0:1], v[2:3]
	v_cvt_pk_bf16_f32 v0, v6, v7
	v_cvt_pk_bf16_f32 v1, v8, v9
	v_cvt_pk_bf16_f32 v2, v10, v11
	v_cvt_pk_bf16_f32 v3, v12, v13
	global_store_dwordx4 v[4:5], v[0:3], off
	s_waitcnt lgkmcnt(0)
	s_barrier
	s_cbranch_scc1 .LBB0_1323
; #define TG_LOAD(A_, B_, KS_) do { const int ks_ = (KS_) < nks ? (KS_) : w; _Pragma("unroll") for (int i = 0; i < 4; ++i) { A_[i] = *(const bf16x8*)(ap + (size_t)i * 16 * K + ks_ * 32); B_[i] = *(const bf16x8*)(bp + (size_t)i * 16 * K + ks_ * 32); } } while (0)
; #define TG_MMA(A_, B_) do { _Pragma("unroll") for (int i = 0; i < 4; ++i) _Pragma("unroll") for (int j = 0; j < 4; ++j) acc[i][j] = __builtin_amdgcn_mfma_f32_16x16x32_bf16(A_[i], B_[j], acc[i][j], 0, 0, 0); } while (0)
; template <int EPI> __device__ __forceinline__ void tail_gemm(LAS unsigned char* lds, const bf16* Am, const bf16* Bt, int K, const TailEpi& E, int tid_in) {
;     ...
;     const int tid = tid_in, lane = tid & 63, w = tid >> 6, l15 = lane & 15, q4 = lane >> 4;
;     const int row0 = MAIN_ROWS + (su >> 4) * 64, col0 = (su & 15) * 64;
;     f32x4 acc[4][4];
; #pragma unroll
;     for (int i = 0; i < 4; ++i)
; #pragma unroll
;         for (int j = 0; j < 4; ++j) acc[i][j] = (f32x4){0.f, 0.f, 0.f, 0.f};
;     const bf16* ap = Am + (size_t)(row0 + l15) * K + q4 * 8;
;     const bf16* bp = Bt + (size_t)(col0 + l15) * K + q4 * 8;
;     {
;         const int nks = K / 32;
;         bf16x8 a0[4], b0[4], a1[4], b1[4], a2[4], b2[4];
;     ...
;         TG_LOAD(a0, b0, w); TG_LOAD(a1, b1, w + 8);
;         for (int ks = w; ks < nks; ks += 24) {
;             TG_LOAD(a2, b2, ks + 16); TG_MMA(a0, b0);
;             if (ks + 8 < nks) { TG_LOAD(a0, b0, ks + 24); TG_MMA(a1, b1); }
;             if (ks + 16 < nks) { TG_LOAD(a1, b1, ks + 32); TG_MMA(a2, b2); }
;         }
;     ...
;     const size_t off = (size_t)row * 1024 + col;
;     if (EPI == 0 || EPI == 1) {
;         const u32x4 s = *(const u32x4*)(E.S + off);
.LBB0_1316:
	s_lshl_b32 s1, s0, 2
	v_mov_b32_e32 v80, v81
	s_andn2_b32 s1, s1, 63
	s_lshl_b32 s2, s0, 6
	v_mov_b32_e32 v82, v81
	v_mov_b32_e32 v83, v81
	v_mov_b64_e32 v[4:5], v[80:81]
	v_mov_b64_e32 v[0:1], v[80:81]
	v_mov_b64_e32 v[20:21], v[80:81]
	v_mov_b64_e32 v[16:17], v[80:81]
	v_mov_b64_e32 v[36:37], v[80:81]
	v_mov_b64_e32 v[32:33], v[80:81]
	v_mov_b64_e32 v[52:53], v[80:81]
	v_mov_b64_e32 v[48:49], v[80:81]
	v_mov_b64_e32 v[60:61], v[80:81]
	v_mov_b64_e32 v[56:57], v[80:81]
	s_waitcnt vmcnt(0)
	v_mov_b64_e32 v[44:45], v[80:81]
	v_mov_b64_e32 v[40:41], v[80:81]
	v_mov_b64_e32 v[28:29], v[80:81]
	v_mov_b64_e32 v[24:25], v[80:81]
	v_mov_b64_e32 v[12:13], v[80:81]
	v_mov_b64_e32 v[8:9], v[80:81]
	s_addk_i32 s1, 0x4000
	s_and_b32 s12, s2, 0x3c0
	v_mov_b64_e32 v[6:7], v[82:83]
	v_mov_b64_e32 v[2:3], v[82:83]
	v_mov_b64_e32 v[22:23], v[82:83]
	v_mov_b64_e32 v[18:19], v[82:83]
	v_mov_b64_e32 v[38:39], v[82:83]
	v_mov_b64_e32 v[34:35], v[82:83]
	v_mov_b64_e32 v[54:55], v[82:83]
	v_mov_b64_e32 v[50:51], v[82:83]
	v_mov_b64_e32 v[62:63], v[82:83]
	v_mov_b64_e32 v[58:59], v[82:83]
	v_mov_b64_e32 v[46:47], v[82:83]
	v_mov_b64_e32 v[42:43], v[82:83]
	v_mov_b64_e32 v[30:31], v[82:83]
	v_mov_b64_e32 v[26:27], v[82:83]
	v_mov_b64_e32 v[14:15], v[82:83]
	v_mov_b64_e32 v[10:11], v[82:83]
	s_and_saveexec_b64 s[2:3], s[38:39]
	s_cbranch_execz .LBB0_1315
	v_or_b32_e32 v0, s1, v177
	v_ashrrev_i32_e32 v1, 31, v0
	v_lshlrev_b64 v[0:1], 10, v[0:1]
	v_lshl_add_u64 v[172:173], v[164:165], 0, v[0:1]
	v_or_b32_e32 v0, s12, v177
	v_lshlrev_b32_e32 v80, 10, v0
	v_lshl_add_u64 v[174:175], v[166:167], 0, v[80:81]
	v_lshlrev_b32_e32 v80, 6, v176
	v_lshl_add_u64 v[172:173], v[172:173], 0, v[80:81]
	v_lshl_add_u64 v[174:175], v[174:175], 0, v[80:81]
	s_mov_b64 s[40:41], 0x4000
	v_mov_b32_e32 v80, v225
	v_lshl_add_u64 v[186:187], v[172:173], 0, s[40:41]
	v_lshl_add_u64 v[188:189], v[174:175], 0, s[40:41]
	v_lshl_add_u64 v[202:203], v[186:187], 0, s[40:41]
	v_lshl_add_u64 v[228:229], v[188:189], 0, s[40:41]
	v_lshl_add_u64 v[234:235], v[202:203], 0, s[40:41]
	v_lshl_add_u64 v[82:83], v[228:229], 0, s[40:41]
	global_load_dwordx4 v[64:67], v[172:173], off
	global_load_dwordx4 v[68:71], v[174:175], off
	global_load_dwordx4 v[72:75], v[186:187], off
	global_load_dwordx4 v[76:79], v[188:189], off
	global_load_dwordx4 v[84:87], v[202:203], off
	global_load_dwordx4 v[88:91], v[228:229], off
	global_load_dwordx4 v[92:95], v[234:235], off
	global_load_dwordx4 v[96:99], v[82:83], off
	global_load_dwordx4 v[100:103], v[172:173], off offset:512
	global_load_dwordx4 v[104:107], v[174:175], off offset:512
	global_load_dwordx4 v[108:111], v[186:187], off offset:512
	global_load_dwordx4 v[112:115], v[188:189], off offset:512
	global_load_dwordx4 v[116:119], v[202:203], off offset:512
	global_load_dwordx4 v[120:123], v[228:229], off offset:512
	global_load_dwordx4 v[124:127], v[234:235], off offset:512
	global_load_dwordx4 v[128:131], v[82:83], off offset:512
	v_add_u32_e32 v172, s1, v178
	v_mov_b32_e32 v173, 0
	v_or_b32_e32 v174, s12, v179
	v_lshlrev_b64 v[186:187], 11, v[172:173]
	v_lshlrev_b32_e32 v188, 1, v174
	v_mov_b32_e32 v189, 0
	v_lshl_add_u64 v[186:187], v[186:187], 0, v[188:189]
	v_lshl_add_u64 v[202:203], s[80:81], 0, v[186:187]
	global_load_dwordx4 v[132:135], v[202:203], off
	s_waitcnt vmcnt(9)
	v_mfma_f32_16x16x32_bf16 v[60:63], v[64:67], v[68:71], v[60:63]
	v_mfma_f32_16x16x32_bf16 v[56:59], v[64:67], v[76:79], v[56:59]
	v_mfma_f32_16x16x32_bf16 v[44:47], v[64:67], v[88:91], v[44:47]
	v_mfma_f32_16x16x32_bf16 v[40:43], v[64:67], v[96:99], v[40:43]
	v_mfma_f32_16x16x32_bf16 v[28:31], v[72:75], v[68:71], v[28:31]
	v_mfma_f32_16x16x32_bf16 v[24:27], v[72:75], v[76:79], v[24:27]
	v_mfma_f32_16x16x32_bf16 v[12:15], v[72:75], v[88:91], v[12:15]
	v_mfma_f32_16x16x32_bf16 v[8:11], v[72:75], v[96:99], v[8:11]
	v_mfma_f32_16x16x32_bf16 v[48:51], v[84:87], v[68:71], v[48:51]
	v_mfma_f32_16x16x32_bf16 v[52:55], v[84:87], v[76:79], v[52:55]
	v_mfma_f32_16x16x32_bf16 v[32:35], v[84:87], v[88:91], v[32:35]
	v_mfma_f32_16x16x32_bf16 v[36:39], v[84:87], v[96:99], v[36:39]
	v_mfma_f32_16x16x32_bf16 v[16:19], v[92:95], v[68:71], v[16:19]
	v_mfma_f32_16x16x32_bf16 v[20:23], v[92:95], v[76:79], v[20:23]
	v_mfma_f32_16x16x32_bf16 v[0:3], v[92:95], v[88:91], v[0:3]
	v_mfma_f32_16x16x32_bf16 v[4:7], v[92:95], v[96:99], v[4:7]
	s_waitcnt vmcnt(1)
	v_mfma_f32_16x16x32_bf16 v[60:63], v[100:103], v[104:107], v[60:63]
	v_mfma_f32_16x16x32_bf16 v[56:59], v[100:103], v[112:115], v[56:59]
	v_mfma_f32_16x16x32_bf16 v[44:47], v[100:103], v[120:123], v[44:47]
	v_mfma_f32_16x16x32_bf16 v[40:43], v[100:103], v[128:131], v[40:43]
	v_mfma_f32_16x16x32_bf16 v[28:31], v[108:111], v[104:107], v[28:31]
	v_mfma_f32_16x16x32_bf16 v[24:27], v[108:111], v[112:115], v[24:27]
	v_mfma_f32_16x16x32_bf16 v[12:15], v[108:111], v[120:123], v[12:15]
	v_mfma_f32_16x16x32_bf16 v[8:11], v[108:111], v[128:131], v[8:11]
	v_mfma_f32_16x16x32_bf16 v[48:51], v[116:119], v[104:107], v[48:51]
	v_mfma_f32_16x16x32_bf16 v[52:55], v[116:119], v[112:115], v[52:55]
	v_mfma_f32_16x16x32_bf16 v[32:35], v[116:119], v[120:123], v[32:35]
	v_mfma_f32_16x16x32_bf16 v[36:39], v[116:119], v[128:131], v[36:39]
	v_mfma_f32_16x16x32_bf16 v[16:19], v[124:127], v[104:107], v[16:19]
	v_mfma_f32_16x16x32_bf16 v[20:23], v[124:127], v[112:115], v[20:23]
	v_mfma_f32_16x16x32_bf16 v[0:3], v[124:127], v[120:123], v[0:3]
	v_mfma_f32_16x16x32_bf16 v[4:7], v[124:127], v[128:131], v[4:7]
	v_mov_b32_e32 v225, v80
	v_mov_b32_e32 v82, v81
	v_mov_b32_e32 v83, v81
	s_branch .LBB0_1315

; #define LAS __attribute__((address_space(3)))
; __device__ __forceinline__ float bflo(unsigned w) { return __uint_as_float(w << 16); }
; __device__ __forceinline__ float bfhi(unsigned w) { return __uint_as_float(w & 0xffff0000u); }
; __device__ __forceinline__ u32x4 pack8(f32x4 a, f32x4 b) { u32x4 w; w.x = cvtpk(a[0], a[1]); w.y = cvtpk(a[2], a[3]); w.z = cvtpk(b[0], b[1]); w.w = cvtpk(b[2], b[3]); return w; }
; #define BAR_LDS() do { asm volatile("s_waitcnt lgkmcnt(0)" ::: "memory"); __builtin_amdgcn_s_barrier(); asm volatile("" ::: "memory"); } while (0)
; template <int EPI> __device__ __forceinline__ void tail_gemm(LAS unsigned char* lds, const bf16* Am, const bf16* Bt, int K, const TailEpi& E, int tid_in) {
;     ...
;     LAS float* part = (LAS float*)lds + (size_t)w * 64 * 65;
; #pragma unroll
;     for (int i = 0; i < 4; ++i)
; #pragma unroll
;         for (int j = 0; j < 4; ++j)
; #pragma unroll
;             for (int r = 0; r < 4; ++r) part[(16 * i + 4 * q4 + r) * 65 + 16 * j + l15] = acc[i][j][r];
;     BAR_LDS();
;     const int rl = tid >> 3, c8 = (tid & 7) * 8, row = row0 + rl, col = col0 + c8;
;     f32x4 v0 = {0.f, 0.f, 0.f, 0.f}, v1 = v0;
; #pragma unroll
;     for (int ww = 0; ww < 8; ++ww) { const LAS float* p = (const LAS float*)lds + (size_t)ww * 64 * 65 + rl * 65 + c8;
;         v0[0] += p[0]; v0[1] += p[1]; v0[2] += p[2]; v0[3] += p[3]; v1[0] += p[4]; v1[1] += p[5]; v1[2] += p[6]; v1[3] += p[7]; }
;     const size_t off = (size_t)row * 1024 + col;
;     if (EPI == 0 || EPI == 1) {
;         const u32x4 s = *(const u32x4*)(E.S + off);
;         v0[0] *= bflo(s.x); v0[1] *= bfhi(s.x); v0[2] *= bflo(s.y); v0[3] *= bfhi(s.y); v1[0] *= bflo(s.z); v1[1] *= bfhi(s.z); v1[2] *= bflo(s.w); v1[3] *= bfhi(s.w);
;         if (EPI == 1) { const u32x4 a = *(const u32x4*)(E.A + off);
;             v0[0] += bflo(a.x); v0[1] += bfhi(a.x); v0[2] += bflo(a.y); v0[3] += bfhi(a.y); v1[0] += bflo(a.z); v1[1] += bfhi(a.z); v1[2] += bflo(a.w); v1[3] += bfhi(a.w); }
;         *(u32x4*)(E.S + off) = pack8(v0, v1);
.LBB0_1350:
	s_or_b64 exec, exec, s[2:3]
	ds_write2_b32 v181, v60, v56 offset1:16
	ds_write2_b32 v181, v61, v57 offset0:65 offset1:81
	ds_write2_b32 v181, v62, v58 offset0:130 offset1:146
	ds_write2_b32 v181, v63, v59 offset0:195 offset1:211
	ds_write2_b32 v181, v44, v40 offset0:32 offset1:48
	ds_write2_b32 v181, v45, v41 offset0:97 offset1:113
	ds_write2_b32 v181, v46, v42 offset0:162 offset1:178
	ds_write2_b32 v181, v47, v43 offset0:227 offset1:243
	v_add_u32_e32 v40, 0x1000, v181
	ds_write2_b32 v40, v28, v24 offset0:16 offset1:32
	ds_write2_b32 v40, v29, v25 offset0:81 offset1:97
	ds_write2_b32 v40, v30, v26 offset0:146 offset1:162
	ds_write2_b32 v40, v31, v27 offset0:211 offset1:227
	ds_write2_b32 v40, v12, v8 offset0:48 offset1:64
	ds_write2_b32 v40, v13, v9 offset0:113 offset1:129
	ds_write2_b32 v40, v14, v10 offset0:178 offset1:194
	v_add_u32_e32 v8, 0x1200, v181
	ds_write2_b32 v8, v15, v11 offset0:115 offset1:131
	v_add_u32_e32 v8, 0x2000, v181
	ds_write2_b32 v8, v48, v52 offset0:32 offset1:48
	ds_write2_b32 v8, v49, v53 offset0:97 offset1:113
	ds_write2_b32 v8, v50, v54 offset0:162 offset1:178
	ds_write2_b32 v8, v51, v55 offset0:227 offset1:243
	ds_write2_b32 v8, v32, v36 offset0:64 offset1:80
	ds_write2_b32 v8, v33, v37 offset0:129 offset1:145
	ds_write2_b32 v8, v34, v38 offset0:194 offset1:210
	v_add_u32_e32 v8, 0x2400, v181
	ds_write2_b32 v8, v35, v39 offset0:3 offset1:19
	v_add_u32_e32 v8, 0x3000, v181
	v_add_u32_e32 v9, 0x3200, v181
	ds_write2_b32 v8, v16, v20 offset0:48 offset1:64
	ds_write2_b32 v8, v17, v21 offset0:113 offset1:129
	ds_write2_b32 v8, v18, v22 offset0:178 offset1:194
	ds_write2_b32 v9, v19, v23 offset0:115 offset1:131
	ds_write2_b32 v8, v0, v4 offset0:80 offset1:96
	ds_write2_b32 v8, v1, v5 offset0:145 offset1:161
	ds_write2_b32 v8, v2, v6 offset0:210 offset1:226
	v_add_u32_e32 v0, 0x3400, v181
	ds_write2_b32 v0, v3, v7 offset0:19 offset1:35
	v_add_u32_e32 v0, s1, v178
	v_ashrrev_i32_e32 v1, 31, v0
	v_or_b32_e32 v2, s12, v179
	v_lshlrev_b64 v[4:5], 11, v[0:1]
	v_lshl_or_b32 v4, v2, 1, v4
	s_waitcnt lgkmcnt(0)
	s_barrier
	v_lshl_add_u64 v[8:9], s[84:85], 0, v[4:5]
	v_lshl_add_u64 v[4:5], s[80:81], 0, v[4:5]
	s_waitcnt vmcnt(0)
	v_mov_b32_e32 v0, v100
	v_mov_b32_e32 v1, v101
	v_mov_b32_e32 v2, v102
	v_mov_b32_e32 v3, v103
	v_add_u32_e32 v18, 0x4100, v180
	s_waitcnt vmcnt(0)
	v_mov_b32_e32 v4, v104
	v_mov_b32_e32 v5, v105
	v_mov_b32_e32 v6, v106
	v_mov_b32_e32 v7, v107
	v_add_u32_e32 v20, 0x8200, v180
	v_add_u32_e32 v22, 0xc300, v180
	ds_read2_b32 v[10:11], v180 offset1:1
	ds_read2_b32 v[12:13], v180 offset0:2 offset1:3
	ds_read2_b32 v[14:15], v180 offset0:4 offset1:5
	ds_read2_b32 v[16:17], v180 offset0:6 offset1:7
	ds_read2_b32 v[18:19], v18 offset1:1
	ds_read2_b32 v[20:21], v20 offset1:1
	ds_read2_b32 v[22:23], v22 offset1:1
	s_waitcnt lgkmcnt(6)
	v_pk_add_f32 v[10:11], v[10:11], 0 op_sel_hi:[1,0]
	v_add_u32_e32 v24, 0x4108, v180
	s_waitcnt lgkmcnt(2)
	v_pk_add_f32 v[10:11], v[10:11], v[18:19]
	ds_read2_b32 v[24:25], v24 offset1:1
	s_waitcnt lgkmcnt(2)
	v_pk_add_f32 v[10:11], v[10:11], v[20:21]
	v_pk_add_f32 v[12:13], v[12:13], 0 op_sel_hi:[1,0]
	s_waitcnt lgkmcnt(1)
	v_pk_add_f32 v[10:11], v[10:11], v[22:23]
	ds_read2_b32 v[18:19], v182 offset1:1
	ds_read2_b32 v[20:21], v190 offset1:1
	ds_read2_b32 v[22:23], v183 offset1:1
	ds_read2_b32 v[26:27], v184 offset1:1
	ds_read2_b32 v[28:29], v185 offset1:1
	s_waitcnt lgkmcnt(4)
	v_pk_add_f32 v[10:11], v[10:11], v[18:19]
	ds_read2_b32 v[18:19], v191 offset1:1
	ds_read2_b32 v[30:31], v192 offset1:1
	ds_read2_b32 v[32:33], v193 offset1:1
	s_waitcnt lgkmcnt(6)
	v_pk_add_f32 v[10:11], v[10:11], v[20:21]
	ds_read2_b32 v[20:21], v194 offset1:1
	ds_read2_b32 v[34:35], v198 offset1:1
	ds_read2_b32 v[36:37], v195 offset1:1
	ds_read2_b32 v[38:39], v196 offset1:1
	ds_read2_b32 v[40:41], v197 offset1:1
	s_waitcnt lgkmcnt(4)
	v_pk_add_f32 v[10:11], v[10:11], v[20:21]
	ds_read2_b32 v[20:21], v199 offset1:1
	ds_read2_b32 v[42:43], v200 offset1:1
	ds_read2_b32 v[44:45], v201 offset1:1
	s_waitcnt lgkmcnt(6)
	v_pk_add_f32 v[10:11], v[10:11], v[34:35]
	v_pk_add_f32 v[12:13], v[12:13], v[24:25]
	s_add_i32 s0, s0, s30
	s_cmpk_gt_i32 s0, 0x9f
	s_waitcnt vmcnt(1)
	v_lshlrev_b32_e32 v34, 16, v0
	v_and_b32_e32 v35, 0xffff0000, v0
	s_waitcnt vmcnt(0)
	v_lshlrev_b32_e32 v46, 16, v4
	v_and_b32_e32 v47, 0xffff0000, v4
	v_add_u32_e32 v0, 0x8208, v180
	v_pk_fma_f32 v[10:11], v[10:11], v[34:35], v[46:47]
	v_add_u32_e32 v4, 0xc308, v180
	ds_read2_b32 v[24:25], v0 offset1:1
	ds_read2_b32 v[34:35], v4 offset1:1
	v_add_u32_e32 v0, 0x4110, v180
	v_add_u32_e32 v4, 0x8210, v180
	ds_read2_b32 v[46:47], v0 offset1:1
	ds_read2_b32 v[48:49], v4 offset1:1
	s_waitcnt lgkmcnt(3)
	v_pk_add_f32 v[12:13], v[12:13], v[24:25]
	v_lshlrev_b32_e32 v0, 16, v1
	s_waitcnt lgkmcnt(2)
	v_pk_add_f32 v[12:13], v[12:13], v[34:35]
	v_and_b32_e32 v1, 0xffff0000, v1
	v_pk_add_f32 v[12:13], v[12:13], v[22:23]
	v_lshlrev_b32_e32 v4, 16, v5
	v_pk_add_f32 v[12:13], v[12:13], v[18:19]
	v_and_b32_e32 v5, 0xffff0000, v5
	v_pk_add_f32 v[12:13], v[12:13], v[36:37]
	v_add_u32_e32 v18, 0x8218, v180
	v_pk_add_f32 v[12:13], v[12:13], v[20:21]
	v_add_u32_e32 v20, 0xc318, v180
	v_pk_fma_f32 v[4:5], v[12:13], v[0:1], v[4:5]
	v_add_u32_e32 v12, 0xc310, v180
	ds_read2_b32 v[12:13], v12 offset1:1
	v_pk_add_f32 v[0:1], v[14:15], 0 op_sel_hi:[1,0]
	v_add_u32_e32 v14, 0x4118, v180
	s_waitcnt lgkmcnt(2)
	v_pk_add_f32 v[0:1], v[0:1], v[46:47]
	ds_read2_b32 v[14:15], v14 offset1:1
	ds_read2_b32 v[18:19], v18 offset1:1
	ds_read2_b32 v[20:21], v20 offset1:1
	s_waitcnt lgkmcnt(4)
	v_pk_add_f32 v[0:1], v[0:1], v[48:49]
	v_lshlrev_b32_e32 v22, 16, v6
	s_waitcnt lgkmcnt(3)
	v_pk_add_f32 v[0:1], v[0:1], v[12:13]
	v_lshlrev_b32_e32 v12, 16, v2
	v_pk_add_f32 v[0:1], v[0:1], v[26:27]
	v_and_b32_e32 v13, 0xffff0000, v2
	v_pk_add_f32 v[0:1], v[0:1], v[30:31]
	v_and_b32_e32 v23, 0xffff0000, v6
	v_pk_add_f32 v[0:1], v[0:1], v[38:39]
	v_lshlrev_b32_e32 v2, 16, v3
	v_pk_add_f32 v[0:1], v[0:1], v[42:43]
	v_and_b32_e32 v3, 0xffff0000, v3
	v_pk_fma_f32 v[12:13], v[0:1], v[12:13], v[22:23]
	v_pk_add_f32 v[0:1], v[16:17], 0 op_sel_hi:[1,0]
	v_lshlrev_b32_e32 v6, 16, v7
	s_waitcnt lgkmcnt(2)
	v_pk_add_f32 v[0:1], v[0:1], v[14:15]
	v_and_b32_e32 v7, 0xffff0000, v7
	s_waitcnt lgkmcnt(1)
	v_pk_add_f32 v[0:1], v[0:1], v[18:19]
	s_waitcnt lgkmcnt(0)
	v_pk_add_f32 v[0:1], v[0:1], v[20:21]
	s_nop 0
	v_pk_add_f32 v[0:1], v[0:1], v[28:29]
	s_nop 0
	v_pk_add_f32 v[0:1], v[0:1], v[32:33]
	s_nop 0
	v_pk_add_f32 v[0:1], v[0:1], v[40:41]
	s_nop 0
	v_pk_add_f32 v[0:1], v[0:1], v[44:45]
	s_nop 0
	v_pk_fma_f32 v[6:7], v[0:1], v[2:3], v[6:7]
	v_cvt_pk_bf16_f32 v0, v10, v11
	v_cvt_pk_bf16_f32 v1, v4, v5
	v_cvt_pk_bf16_f32 v2, v12, v13
	v_cvt_pk_bf16_f32 v3, v6, v7
	global_store_dwordx4 v[8:9], v[0:3], off
	s_waitcnt lgkmcnt(0)
	s_barrier
	s_cbranch_scc1 .LBB0_1358
; #define TG_LOAD(A_, B_, KS_) do { const int ks_ = (KS_) < nks ? (KS_) : w; _Pragma("unroll") for (int i = 0; i < 4; ++i) { A_[i] = *(const bf16x8*)(ap + (size_t)i * 16 * K + ks_ * 32); B_[i] = *(const bf16x8*)(bp + (size_t)i * 16 * K + ks_ * 32); } } while (0)
; template <int EPI> __device__ __forceinline__ void tail_gemm(LAS unsigned char* lds, const bf16* Am, const bf16* Bt, int K, const TailEpi& E, int tid_in) {
;     ...
;     const int tid = tid_in, lane = tid & 63, w = tid >> 6, l15 = lane & 15, q4 = lane >> 4;
;     const int row0 = MAIN_ROWS + (su >> 4) * 64, col0 = (su & 15) * 64;
;     f32x4 acc[4][4];
; #pragma unroll
;     for (int i = 0; i < 4; ++i)
; #pragma unroll
;         for (int j = 0; j < 4; ++j) acc[i][j] = (f32x4){0.f, 0.f, 0.f, 0.f};
;     const bf16* ap = Am + (size_t)(row0 + l15) * K + q4 * 8;
;     const bf16* bp = Bt + (size_t)(col0 + l15) * K + q4 * 8;
;     {
;         const int nks = K / 32;
;         bf16x8 a0[4], b0[4], a1[4], b1[4], a2[4], b2[4];
;     ...
;         TG_LOAD(a0, b0, w); TG_LOAD(a1, b1, w + 8);
;         for (int ks = w; ks < nks; ks += 24) {
.LBB0_1351:
	s_lshl_b32 s1, s0, 2
	v_mov_b32_e32 v80, v81
	s_andn2_b32 s1, s1, 63
	s_lshl_b32 s2, s0, 6
	v_mov_b32_e32 v82, v81
	v_mov_b32_e32 v83, v81
	v_mov_b64_e32 v[4:5], v[80:81]
	v_mov_b64_e32 v[0:1], v[80:81]
	v_mov_b64_e32 v[20:21], v[80:81]
	v_mov_b64_e32 v[16:17], v[80:81]
	v_mov_b64_e32 v[36:37], v[80:81]
	v_mov_b64_e32 v[32:33], v[80:81]
	v_mov_b64_e32 v[52:53], v[80:81]
	v_mov_b64_e32 v[48:49], v[80:81]
	v_mov_b64_e32 v[60:61], v[80:81]
	v_mov_b64_e32 v[56:57], v[80:81]
	s_waitcnt vmcnt(0)
	v_mov_b64_e32 v[44:45], v[80:81]
	v_mov_b64_e32 v[40:41], v[80:81]
	v_mov_b64_e32 v[28:29], v[80:81]
	v_mov_b64_e32 v[24:25], v[80:81]
	v_mov_b64_e32 v[12:13], v[80:81]
	v_mov_b64_e32 v[8:9], v[80:81]
	s_addk_i32 s1, 0x4000
	s_and_b32 s12, s2, 0x3c0
	v_mov_b64_e32 v[6:7], v[82:83]
	v_mov_b64_e32 v[2:3], v[82:83]
	v_mov_b64_e32 v[22:23], v[82:83]
	v_mov_b64_e32 v[18:19], v[82:83]
	v_mov_b64_e32 v[38:39], v[82:83]
	v_mov_b64_e32 v[34:35], v[82:83]
	v_mov_b64_e32 v[54:55], v[82:83]
	v_mov_b64_e32 v[50:51], v[82:83]
	v_mov_b64_e32 v[62:63], v[82:83]
	v_mov_b64_e32 v[58:59], v[82:83]
	v_mov_b64_e32 v[46:47], v[82:83]
	v_mov_b64_e32 v[42:43], v[82:83]
	v_mov_b64_e32 v[30:31], v[82:83]
	v_mov_b64_e32 v[26:27], v[82:83]
	v_mov_b64_e32 v[14:15], v[82:83]
	v_mov_b64_e32 v[10:11], v[82:83]
	s_and_saveexec_b64 s[2:3], s[38:39]
	s_cbranch_execz .LBB0_1350
	v_or_b32_e32 v0, s1, v177
	v_ashrrev_i32_e32 v1, 31, v0
	v_lshlrev_b64 v[0:1], 11, v[0:1]
	v_lshl_add_u64 v[172:173], v[164:165], 0, v[0:1]
	v_or_b32_e32 v0, s12, v177
	v_lshlrev_b32_e32 v80, 11, v0
	v_lshl_add_u64 v[174:175], v[166:167], 0, v[80:81]
	v_lshlrev_b32_e32 v80, 6, v176
	v_lshl_add_u64 v[172:173], v[172:173], 0, v[80:81]
	v_lshl_add_u64 v[174:175], v[174:175], 0, v[80:81]
	s_mov_b64 s[40:41], 0x8000
	v_mov_b32_e32 v80, v225
	v_lshl_add_u64 v[186:187], v[172:173], 0, s[40:41]
	v_lshl_add_u64 v[188:189], v[174:175], 0, s[40:41]
	v_lshl_add_u64 v[202:203], v[186:187], 0, s[40:41]
	v_lshl_add_u64 v[228:229], v[188:189], 0, s[40:41]
	v_lshl_add_u64 v[234:235], v[202:203], 0, s[40:41]
	v_lshl_add_u64 v[82:83], v[228:229], 0, s[40:41]
	global_load_dwordx4 v[64:67], v[172:173], off
	global_load_dwordx4 v[68:71], v[174:175], off
	global_load_dwordx4 v[72:75], v[186:187], off
	global_load_dwordx4 v[76:79], v[188:189], off
	global_load_dwordx4 v[84:87], v[202:203], off
	global_load_dwordx4 v[88:91], v[228:229], off
	global_load_dwordx4 v[92:95], v[234:235], off
	global_load_dwordx4 v[96:99], v[82:83], off
	global_load_dwordx4 v[100:103], v[172:173], off offset:512
	global_load_dwordx4 v[104:107], v[174:175], off offset:512
	global_load_dwordx4 v[108:111], v[186:187], off offset:512
	global_load_dwordx4 v[112:115], v[188:189], off offset:512
	global_load_dwordx4 v[116:119], v[202:203], off offset:512
	global_load_dwordx4 v[120:123], v[228:229], off offset:512
	global_load_dwordx4 v[124:127], v[234:235], off offset:512
	global_load_dwordx4 v[128:131], v[82:83], off offset:512
	global_load_dwordx4 v[132:135], v[172:173], off offset:1024
	global_load_dwordx4 v[136:139], v[174:175], off offset:1024
	global_load_dwordx4 v[140:143], v[186:187], off offset:1024
	global_load_dwordx4 v[144:147], v[188:189], off offset:1024
	global_load_dwordx4 v[148:151], v[202:203], off offset:1024
	global_load_dwordx4 v[152:155], v[228:229], off offset:1024
	global_load_dwordx4 v[156:159], v[234:235], off offset:1024
	global_load_dwordx4 v[160:163], v[82:83], off offset:1024
	global_load_dwordx4 v[204:207], v[172:173], off offset:1536
	global_load_dwordx4 v[208:211], v[174:175], off offset:1536
	global_load_dwordx4 v[212:215], v[186:187], off offset:1536
	global_load_dwordx4 v[224:227], v[188:189], off offset:1536
	global_load_dwordx4 v[236:239], v[202:203], off offset:1536
	global_load_dwordx4 v[240:243], v[228:229], off offset:1536
	global_load_dwordx4 v[244:247], v[234:235], off offset:1536
	global_load_dwordx4 v[248:251], v[82:83], off offset:1536
	s_waitcnt vmcnt(24)
; __device__ __forceinline__ float bflo(unsigned w) { return __uint_as_float(w << 16); }
; __device__ __forceinline__ float bfhi(unsigned w) { return __uint_as_float(w & 0xffff0000u); }
; #define TG_LOAD(A_, B_, KS_) do { const int ks_ = (KS_) < nks ? (KS_) : w; _Pragma("unroll") for (int i = 0; i < 4; ++i) { A_[i] = *(const bf16x8*)(ap + (size_t)i * 16 * K + ks_ * 32); B_[i] = *(const bf16x8*)(bp + (size_t)i * 16 * K + ks_ * 32); } } while (0)
; #define TG_MMA(A_, B_) do { _Pragma("unroll") for (int i = 0; i < 4; ++i) _Pragma("unroll") for (int j = 0; j < 4; ++j) acc[i][j] = __builtin_amdgcn_mfma_f32_16x16x32_bf16(A_[i], B_[j], acc[i][j], 0, 0, 0); } while (0)
; template <int EPI> __device__ __forceinline__ void tail_gemm(LAS unsigned char* lds, const bf16* Am, const bf16* Bt, int K, const TailEpi& E, int tid_in) {
;     ...
;         TG_LOAD(a0, b0, w); TG_LOAD(a1, b1, w + 8);
;         for (int ks = w; ks < nks; ks += 24) {
;             TG_LOAD(a2, b2, ks + 16); TG_MMA(a0, b0);
;             if (ks + 8 < nks) { TG_LOAD(a0, b0, ks + 24); TG_MMA(a1, b1); }
;             if (ks + 16 < nks) { TG_LOAD(a1, b1, ks + 32); TG_MMA(a2, b2); }
;         }
;     ...
;     const size_t off = (size_t)row * 1024 + col;
;     if (EPI == 0 || EPI == 1) {
;         const u32x4 s = *(const u32x4*)(E.S + off);
;         v0[0] *= bflo(s.x); v0[1] *= bfhi(s.x); v0[2] *= bflo(s.y); v0[3] *= bfhi(s.y); v1[0] *= bflo(s.z); v1[1] *= bfhi(s.z); v1[2] *= bflo(s.w); v1[3] *= bfhi(s.w);
;         if (EPI == 1) { const u32x4 a = *(const u32x4*)(E.A + off);
	v_mfma_f32_16x16x32_bf16 v[60:63], v[64:67], v[68:71], v[60:63]
	v_mfma_f32_16x16x32_bf16 v[56:59], v[64:67], v[76:79], v[56:59]
	v_mfma_f32_16x16x32_bf16 v[44:47], v[64:67], v[88:91], v[44:47]
	v_mfma_f32_16x16x32_bf16 v[40:43], v[64:67], v[96:99], v[40:43]
	v_mfma_f32_16x16x32_bf16 v[28:31], v[72:75], v[68:71], v[28:31]
	v_mfma_f32_16x16x32_bf16 v[24:27], v[72:75], v[76:79], v[24:27]
	v_mfma_f32_16x16x32_bf16 v[12:15], v[72:75], v[88:91], v[12:15]
	v_mfma_f32_16x16x32_bf16 v[8:11], v[72:75], v[96:99], v[8:11]
	v_mfma_f32_16x16x32_bf16 v[48:51], v[84:87], v[68:71], v[48:51]
	v_mfma_f32_16x16x32_bf16 v[52:55], v[84:87], v[76:79], v[52:55]
	v_mfma_f32_16x16x32_bf16 v[32:35], v[84:87], v[88:91], v[32:35]
	v_mfma_f32_16x16x32_bf16 v[36:39], v[84:87], v[96:99], v[36:39]
	v_mfma_f32_16x16x32_bf16 v[16:19], v[92:95], v[68:71], v[16:19]
	v_mfma_f32_16x16x32_bf16 v[20:23], v[92:95], v[76:79], v[20:23]
	v_mfma_f32_16x16x32_bf16 v[0:3], v[92:95], v[88:91], v[0:3]
	v_mfma_f32_16x16x32_bf16 v[4:7], v[92:95], v[96:99], v[4:7]
	s_waitcnt vmcnt(16)
	v_mfma_f32_16x16x32_bf16 v[60:63], v[100:103], v[104:107], v[60:63]
	v_mfma_f32_16x16x32_bf16 v[56:59], v[100:103], v[112:115], v[56:59]
	v_mfma_f32_16x16x32_bf16 v[44:47], v[100:103], v[120:123], v[44:47]
	v_mfma_f32_16x16x32_bf16 v[40:43], v[100:103], v[128:131], v[40:43]
	v_mfma_f32_16x16x32_bf16 v[28:31], v[108:111], v[104:107], v[28:31]
	v_mfma_f32_16x16x32_bf16 v[24:27], v[108:111], v[112:115], v[24:27]
	v_mfma_f32_16x16x32_bf16 v[12:15], v[108:111], v[120:123], v[12:15]
	v_mfma_f32_16x16x32_bf16 v[8:11], v[108:111], v[128:131], v[8:11]
	v_mfma_f32_16x16x32_bf16 v[48:51], v[116:119], v[104:107], v[48:51]
	v_mfma_f32_16x16x32_bf16 v[52:55], v[116:119], v[112:115], v[52:55]
	v_mfma_f32_16x16x32_bf16 v[32:35], v[116:119], v[120:123], v[32:35]
	v_mfma_f32_16x16x32_bf16 v[36:39], v[116:119], v[128:131], v[36:39]
	v_mfma_f32_16x16x32_bf16 v[16:19], v[124:127], v[104:107], v[16:19]
	v_mfma_f32_16x16x32_bf16 v[20:23], v[124:127], v[112:115], v[20:23]
	v_mfma_f32_16x16x32_bf16 v[0:3], v[124:127], v[120:123], v[0:3]
	v_mfma_f32_16x16x32_bf16 v[4:7], v[124:127], v[128:131], v[4:7]
	s_waitcnt vmcnt(8)
	v_mfma_f32_16x16x32_bf16 v[60:63], v[132:135], v[136:139], v[60:63]
	v_mfma_f32_16x16x32_bf16 v[56:59], v[132:135], v[144:147], v[56:59]
	v_mfma_f32_16x16x32_bf16 v[44:47], v[132:135], v[152:155], v[44:47]
	v_mfma_f32_16x16x32_bf16 v[40:43], v[132:135], v[160:163], v[40:43]
	v_mfma_f32_16x16x32_bf16 v[28:31], v[140:143], v[136:139], v[28:31]
	v_mfma_f32_16x16x32_bf16 v[24:27], v[140:143], v[144:147], v[24:27]
	v_mfma_f32_16x16x32_bf16 v[12:15], v[140:143], v[152:155], v[12:15]
	v_mfma_f32_16x16x32_bf16 v[8:11], v[140:143], v[160:163], v[8:11]
	v_mfma_f32_16x16x32_bf16 v[48:51], v[148:151], v[136:139], v[48:51]
	v_mfma_f32_16x16x32_bf16 v[52:55], v[148:151], v[144:147], v[52:55]
	v_mfma_f32_16x16x32_bf16 v[32:35], v[148:151], v[152:155], v[32:35]
	v_mfma_f32_16x16x32_bf16 v[36:39], v[148:151], v[160:163], v[36:39]
	v_mfma_f32_16x16x32_bf16 v[16:19], v[156:159], v[136:139], v[16:19]
	v_mfma_f32_16x16x32_bf16 v[20:23], v[156:159], v[144:147], v[20:23]
	v_mfma_f32_16x16x32_bf16 v[0:3], v[156:159], v[152:155], v[0:3]
	v_mfma_f32_16x16x32_bf16 v[4:7], v[156:159], v[160:163], v[4:7]
	v_add_u32_e32 v172, s1, v178
	v_mov_b32_e32 v173, 0
	v_or_b32_e32 v174, s12, v179
	v_lshlrev_b64 v[186:187], 11, v[172:173]
	v_lshlrev_b32_e32 v188, 1, v174
	v_mov_b32_e32 v189, 0
	v_lshl_add_u64 v[186:187], v[186:187], 0, v[188:189]
	v_lshl_add_u64 v[202:203], s[84:85], 0, v[186:187]
	global_load_dwordx4 v[100:103], v[202:203], off
	v_lshl_add_u64 v[202:203], s[80:81], 0, v[186:187]
	global_load_dwordx4 v[104:107], v[202:203], off
	s_waitcnt vmcnt(2)
	v_mfma_f32_16x16x32_bf16 v[60:63], v[204:207], v[208:211], v[60:63]
	v_mfma_f32_16x16x32_bf16 v[56:59], v[204:207], v[224:227], v[56:59]
	v_mfma_f32_16x16x32_bf16 v[44:47], v[204:207], v[240:243], v[44:47]
	v_mfma_f32_16x16x32_bf16 v[40:43], v[204:207], v[248:251], v[40:43]
	v_mfma_f32_16x16x32_bf16 v[28:31], v[212:215], v[208:211], v[28:31]
	v_mfma_f32_16x16x32_bf16 v[24:27], v[212:215], v[224:227], v[24:27]
	v_mfma_f32_16x16x32_bf16 v[12:15], v[212:215], v[240:243], v[12:15]
	v_mfma_f32_16x16x32_bf16 v[8:11], v[212:215], v[248:251], v[8:11]
	v_mfma_f32_16x16x32_bf16 v[48:51], v[236:239], v[208:211], v[48:51]
	v_mfma_f32_16x16x32_bf16 v[52:55], v[236:239], v[224:227], v[52:55]
	v_mfma_f32_16x16x32_bf16 v[32:35], v[236:239], v[240:243], v[32:35]
	v_mfma_f32_16x16x32_bf16 v[36:39], v[236:239], v[248:251], v[36:39]
	v_mfma_f32_16x16x32_bf16 v[16:19], v[244:247], v[208:211], v[16:19]
	v_mfma_f32_16x16x32_bf16 v[20:23], v[244:247], v[224:227], v[20:23]
	v_mfma_f32_16x16x32_bf16 v[0:3], v[244:247], v[240:243], v[0:3]
	v_mfma_f32_16x16x32_bf16 v[4:7], v[244:247], v[248:251], v[4:7]
	v_mov_b32_e32 v225, v80
	v_mov_b32_e32 v82, v81
	v_mov_b32_e32 v83, v81
	s_branch .LBB0_1350

; #define TG_LOAD(A_, B_, KS_) do { const int ks_ = (KS_) < nks ? (KS_) : w; _Pragma("unroll") for (int i = 0; i < 4; ++i) { A_[i] = *(const bf16x8*)(ap + (size_t)i * 16 * K + ks_ * 32); B_[i] = *(const bf16x8*)(bp + (size_t)i * 16 * K + ks_ * 32); } } while (0)
; template <int EPI> __device__ __forceinline__ void tail_gemm(LAS unsigned char* lds, const bf16* Am, const bf16* Bt, int K, const TailEpi& E, int tid_in) {
;     ...
;     const int tid = tid_in, lane = tid & 63, w = tid >> 6, l15 = lane & 15, q4 = lane >> 4;
;     const int row0 = MAIN_ROWS + (su >> 4) * 64, col0 = (su & 15) * 64;
;     f32x4 acc[4][4];
; #pragma unroll
;     for (int i = 0; i < 4; ++i)
; #pragma unroll
;         for (int j = 0; j < 4; ++j) acc[i][j] = (f32x4){0.f, 0.f, 0.f, 0.f};
;     const bf16* ap = Am + (size_t)(row0 + l15) * K + q4 * 8;
;     const bf16* bp = Bt + (size_t)(col0 + l15) * K + q4 * 8;
;     {
;         const int nks = K / 32;
;         bf16x8 a0[4], b0[4], a1[4], b1[4], a2[4], b2[4];
;     ...
;         TG_LOAD(a0, b0, w); TG_LOAD(a1, b1, w + 8);
;         for (int ks = w; ks < nks; ks += 24) {
.LBB0_1520:
	s_lshl_b32 s0, s12, 2
	v_mov_b32_e32 v80, v81
	s_and_b32 s1, s0, 0xffffffc0
	s_and_b32 s13, s12, 15
	v_mov_b32_e32 v82, v81
	v_mov_b32_e32 v83, v81
	s_waitcnt lgkmcnt(0)
	v_mov_b64_e32 v[4:5], v[80:81]
	v_mov_b64_e32 v[0:1], v[80:81]
	v_mov_b64_e32 v[20:21], v[80:81]
	v_mov_b64_e32 v[16:17], v[80:81]
	v_mov_b64_e32 v[36:37], v[80:81]
	v_mov_b64_e32 v[32:33], v[80:81]
	v_mov_b64_e32 v[52:53], v[80:81]
	v_mov_b64_e32 v[48:49], v[80:81]
	v_mov_b64_e32 v[60:61], v[80:81]
	v_mov_b64_e32 v[56:57], v[80:81]
	s_waitcnt vmcnt(0)
	v_mov_b64_e32 v[44:45], v[80:81]
	v_mov_b64_e32 v[40:41], v[80:81]
	v_mov_b64_e32 v[28:29], v[80:81]
	v_mov_b64_e32 v[24:25], v[80:81]
	v_mov_b64_e32 v[12:13], v[80:81]
	v_mov_b64_e32 v[8:9], v[80:81]
	s_addk_i32 s1, 0x4000
	s_lshl_b32 s0, s13, 6
	v_mov_b64_e32 v[6:7], v[82:83]
	v_mov_b64_e32 v[2:3], v[82:83]
	v_mov_b64_e32 v[22:23], v[82:83]
	v_mov_b64_e32 v[18:19], v[82:83]
	v_mov_b64_e32 v[38:39], v[82:83]
	v_mov_b64_e32 v[34:35], v[82:83]
	v_mov_b64_e32 v[54:55], v[82:83]
	v_mov_b64_e32 v[50:51], v[82:83]
	v_mov_b64_e32 v[62:63], v[82:83]
	v_mov_b64_e32 v[58:59], v[82:83]
	v_mov_b64_e32 v[46:47], v[82:83]
	v_mov_b64_e32 v[42:43], v[82:83]
	v_mov_b64_e32 v[30:31], v[82:83]
	v_mov_b64_e32 v[26:27], v[82:83]
	v_mov_b64_e32 v[14:15], v[82:83]
	v_mov_b64_e32 v[10:11], v[82:83]
	s_and_saveexec_b64 s[4:5], s[38:39]
	s_cbranch_execz .LBB0_1528
	v_or_b32_e32 v0, s1, v177
	v_ashrrev_i32_e32 v1, 31, v0
	v_lshlrev_b64 v[0:1], 11, v[0:1]
	v_lshl_add_u64 v[172:173], v[164:165], 0, v[0:1]
	v_or_b32_e32 v0, s0, v177
	v_lshlrev_b32_e32 v80, 11, v0
	v_lshl_add_u64 v[174:175], v[166:167], 0, v[80:81]
	v_lshlrev_b32_e32 v80, 6, v176
	v_lshl_add_u64 v[172:173], v[172:173], 0, v[80:81]
	v_lshl_add_u64 v[174:175], v[174:175], 0, v[80:81]
	s_mov_b64 s[42:43], 0x8000
	v_mov_b32_e32 v80, v225
	v_lshl_add_u64 v[186:187], v[172:173], 0, s[42:43]
	v_lshl_add_u64 v[188:189], v[174:175], 0, s[42:43]
	v_lshl_add_u64 v[202:203], v[186:187], 0, s[42:43]
	v_lshl_add_u64 v[228:229], v[188:189], 0, s[42:43]
	v_lshl_add_u64 v[234:235], v[202:203], 0, s[42:43]
	v_lshl_add_u64 v[82:83], v[228:229], 0, s[42:43]
	global_load_dwordx4 v[64:67], v[172:173], off
	global_load_dwordx4 v[68:71], v[174:175], off
	global_load_dwordx4 v[72:75], v[186:187], off
	global_load_dwordx4 v[76:79], v[188:189], off
	global_load_dwordx4 v[84:87], v[202:203], off
	global_load_dwordx4 v[88:91], v[228:229], off
	global_load_dwordx4 v[92:95], v[234:235], off
	global_load_dwordx4 v[96:99], v[82:83], off
	global_load_dwordx4 v[100:103], v[172:173], off offset:512
	global_load_dwordx4 v[104:107], v[174:175], off offset:512
	global_load_dwordx4 v[108:111], v[186:187], off offset:512
	global_load_dwordx4 v[112:115], v[188:189], off offset:512
	global_load_dwordx4 v[116:119], v[202:203], off offset:512
	global_load_dwordx4 v[120:123], v[228:229], off offset:512
	global_load_dwordx4 v[124:127], v[234:235], off offset:512
	global_load_dwordx4 v[128:131], v[82:83], off offset:512
	global_load_dwordx4 v[132:135], v[172:173], off offset:1024
	global_load_dwordx4 v[136:139], v[174:175], off offset:1024
	global_load_dwordx4 v[140:143], v[186:187], off offset:1024
	global_load_dwordx4 v[144:147], v[188:189], off offset:1024
	global_load_dwordx4 v[148:151], v[202:203], off offset:1024
	global_load_dwordx4 v[152:155], v[228:229], off offset:1024
	global_load_dwordx4 v[156:159], v[234:235], off offset:1024
	global_load_dwordx4 v[160:163], v[82:83], off offset:1024
	global_load_dwordx4 v[204:207], v[172:173], off offset:1536
	global_load_dwordx4 v[208:211], v[174:175], off offset:1536
	global_load_dwordx4 v[212:215], v[186:187], off offset:1536
	global_load_dwordx4 v[224:227], v[188:189], off offset:1536
	global_load_dwordx4 v[236:239], v[202:203], off offset:1536
	global_load_dwordx4 v[240:243], v[228:229], off offset:1536
	global_load_dwordx4 v[244:247], v[234:235], off offset:1536
	global_load_dwordx4 v[248:251], v[82:83], off offset:1536
	s_waitcnt vmcnt(24)
	v_mfma_f32_16x16x32_bf16 v[60:63], v[64:67], v[68:71], v[60:63]
	v_mfma_f32_16x16x32_bf16 v[56:59], v[64:67], v[76:79], v[56:59]
	v_mfma_f32_16x16x32_bf16 v[44:47], v[64:67], v[88:91], v[44:47]
	v_mfma_f32_16x16x32_bf16 v[40:43], v[64:67], v[96:99], v[40:43]
	v_mfma_f32_16x16x32_bf16 v[28:31], v[72:75], v[68:71], v[28:31]
	v_mfma_f32_16x16x32_bf16 v[24:27], v[72:75], v[76:79], v[24:27]
	v_mfma_f32_16x16x32_bf16 v[12:15], v[72:75], v[88:91], v[12:15]
	v_mfma_f32_16x16x32_bf16 v[8:11], v[72:75], v[96:99], v[8:11]
	v_mfma_f32_16x16x32_bf16 v[48:51], v[84:87], v[68:71], v[48:51]
	v_mfma_f32_16x16x32_bf16 v[52:55], v[84:87], v[76:79], v[52:55]
	v_mfma_f32_16x16x32_bf16 v[32:35], v[84:87], v[88:91], v[32:35]
	v_mfma_f32_16x16x32_bf16 v[36:39], v[84:87], v[96:99], v[36:39]
	v_mfma_f32_16x16x32_bf16 v[16:19], v[92:95], v[68:71], v[16:19]
	v_mfma_f32_16x16x32_bf16 v[20:23], v[92:95], v[76:79], v[20:23]
	v_mfma_f32_16x16x32_bf16 v[0:3], v[92:95], v[88:91], v[0:3]
	v_mfma_f32_16x16x32_bf16 v[4:7], v[92:95], v[96:99], v[4:7]
	s_waitcnt vmcnt(16)
	v_mfma_f32_16x16x32_bf16 v[60:63], v[100:103], v[104:107], v[60:63]
	v_mfma_f32_16x16x32_bf16 v[56:59], v[100:103], v[112:115], v[56:59]
	v_mfma_f32_16x16x32_bf16 v[44:47], v[100:103], v[120:123], v[44:47]
	v_mfma_f32_16x16x32_bf16 v[40:43], v[100:103], v[128:131], v[40:43]
	v_mfma_f32_16x16x32_bf16 v[28:31], v[108:111], v[104:107], v[28:31]
	v_mfma_f32_16x16x32_bf16 v[24:27], v[108:111], v[112:115], v[24:27]
	v_mfma_f32_16x16x32_bf16 v[12:15], v[108:111], v[120:123], v[12:15]
	v_mfma_f32_16x16x32_bf16 v[8:11], v[108:111], v[128:131], v[8:11]
	v_mfma_f32_16x16x32_bf16 v[48:51], v[116:119], v[104:107], v[48:51]
	v_mfma_f32_16x16x32_bf16 v[52:55], v[116:119], v[112:115], v[52:55]
	v_mfma_f32_16x16x32_bf16 v[32:35], v[116:119], v[120:123], v[32:35]
	v_mfma_f32_16x16x32_bf16 v[36:39], v[116:119], v[128:131], v[36:39]
	v_mfma_f32_16x16x32_bf16 v[16:19], v[124:127], v[104:107], v[16:19]
	v_mfma_f32_16x16x32_bf16 v[20:23], v[124:127], v[112:115], v[20:23]
	v_mfma_f32_16x16x32_bf16 v[0:3], v[124:127], v[120:123], v[0:3]
	v_mfma_f32_16x16x32_bf16 v[4:7], v[124:127], v[128:131], v[4:7]
	s_waitcnt vmcnt(8)
; #define LAS __attribute__((address_space(3)))
; __device__ __forceinline__ float bflo(unsigned w) { return __uint_as_float(w << 16); }
; __device__ __forceinline__ float bfhi(unsigned w) { return __uint_as_float(w & 0xffff0000u); }
; #define BAR_LDS() do { asm volatile("s_waitcnt lgkmcnt(0)" ::: "memory"); __builtin_amdgcn_s_barrier(); asm volatile("" ::: "memory"); } while (0)
; #define TG_LOAD(A_, B_, KS_) do { const int ks_ = (KS_) < nks ? (KS_) : w; _Pragma("unroll") for (int i = 0; i < 4; ++i) { A_[i] = *(const bf16x8*)(ap + (size_t)i * 16 * K + ks_ * 32); B_[i] = *(const bf16x8*)(bp + (size_t)i * 16 * K + ks_ * 32); } } while (0)
; #define TG_MMA(A_, B_) do { _Pragma("unroll") for (int i = 0; i < 4; ++i) _Pragma("unroll") for (int j = 0; j < 4; ++j) acc[i][j] = __builtin_amdgcn_mfma_f32_16x16x32_bf16(A_[i], B_[j], acc[i][j], 0, 0, 0); } while (0)
; template <int EPI> __device__ __forceinline__ void tail_gemm(LAS unsigned char* lds, const bf16* Am, const bf16* Bt, int K, const TailEpi& E, int tid_in) {
;     ...
;         for (int ks = w; ks < nks; ks += 24) {
;             TG_LOAD(a2, b2, ks + 16); TG_MMA(a0, b0);
;             if (ks + 8 < nks) { TG_LOAD(a0, b0, ks + 24); TG_MMA(a1, b1); }
;             if (ks + 16 < nks) { TG_LOAD(a1, b1, ks + 32); TG_MMA(a2, b2); }
;         }
;     ...
;     }
;     LAS float* part = (LAS float*)lds + (size_t)w * 64 * 65;
; #pragma unroll
;     for (int i = 0; i < 4; ++i)
; #pragma unroll
;         for (int j = 0; j < 4; ++j)
; #pragma unroll
;             for (int r = 0; r < 4; ++r) part[(16 * i + 4 * q4 + r) * 65 + 16 * j + l15] = acc[i][j][r];
;     BAR_LDS();
;     ...
;     } else {
;         const u32x4 zw = *(const u32x4*)(E.ZB + off);
;         f32x4 x0 = {bflo(zw.x), bfhi(zw.x), bflo(zw.y), bfhi(zw.y)}, x1 = {bflo(zw.z), bfhi(zw.z), bflo(zw.w), bfhi(zw.w)};
;         if (E.pst) {
;             const f32x4* sp = (const f32x4*)(E.pst + (size_t)row * 32); float s = 0.f, q = 0.f;
	v_mfma_f32_16x16x32_bf16 v[60:63], v[132:135], v[136:139], v[60:63]
	v_mfma_f32_16x16x32_bf16 v[56:59], v[132:135], v[144:147], v[56:59]
	v_mfma_f32_16x16x32_bf16 v[44:47], v[132:135], v[152:155], v[44:47]
	v_mfma_f32_16x16x32_bf16 v[40:43], v[132:135], v[160:163], v[40:43]
	v_mfma_f32_16x16x32_bf16 v[28:31], v[140:143], v[136:139], v[28:31]
	v_mfma_f32_16x16x32_bf16 v[24:27], v[140:143], v[144:147], v[24:27]
	v_mfma_f32_16x16x32_bf16 v[12:15], v[140:143], v[152:155], v[12:15]
	v_mfma_f32_16x16x32_bf16 v[8:11], v[140:143], v[160:163], v[8:11]
	v_mfma_f32_16x16x32_bf16 v[48:51], v[148:151], v[136:139], v[48:51]
	v_mfma_f32_16x16x32_bf16 v[52:55], v[148:151], v[144:147], v[52:55]
	v_mfma_f32_16x16x32_bf16 v[32:35], v[148:151], v[152:155], v[32:35]
	v_mfma_f32_16x16x32_bf16 v[36:39], v[148:151], v[160:163], v[36:39]
	v_mfma_f32_16x16x32_bf16 v[16:19], v[156:159], v[136:139], v[16:19]
	v_mfma_f32_16x16x32_bf16 v[20:23], v[156:159], v[144:147], v[20:23]
	v_mfma_f32_16x16x32_bf16 v[0:3], v[156:159], v[152:155], v[0:3]
	v_mfma_f32_16x16x32_bf16 v[4:7], v[156:159], v[160:163], v[4:7]
	v_add_u32_e32 v172, s1, v178
	v_mov_b32_e32 v173, 0
	v_or_b32_e32 v174, s0, v179
	v_lshlrev_b64 v[186:187], 11, v[172:173]
	v_lshlrev_b32_e32 v188, 1, v174
	v_mov_b32_e32 v189, 0
	v_lshl_add_u64 v[186:187], v[186:187], 0, v[188:189]
	v_lshl_add_u64 v[202:203], s[20:21], 0, v[186:187]
	global_load_dwordx4 v[100:103], v[202:203], off
	v_lshlrev_b32_e32 v234, 2, v174
	global_load_dwordx4 v[136:139], v234, s[48:49] offset:16
	global_load_dwordx4 v[140:143], v234, s[48:49]
	global_load_dwordx4 v[144:147], v234, s[50:51] offset:16
	global_load_dwordx4 v[148:151], v234, s[50:51]
	s_cmp_lg_u64 s[46:47], 0
	s_cbranch_scc0 .Ltl2_ns
	v_lshlrev_b64 v[228:229], 7, v[172:173]
	v_lshl_add_u64 v[228:229], s[46:47], 0, v[228:229]
	global_load_dwordx4 v[104:107], v[228:229], off offset:48
	global_load_dwordx4 v[108:111], v[228:229], off offset:32
	global_load_dwordx4 v[112:115], v[228:229], off offset:16
	global_load_dwordx4 v[116:119], v[228:229], off
	global_load_dwordx4 v[120:123], v[228:229], off offset:112
	global_load_dwordx4 v[124:127], v[228:229], off offset:96
	global_load_dwordx4 v[128:131], v[228:229], off offset:80
	global_load_dwordx4 v[132:135], v[228:229], off offset:64
	s_waitcnt vmcnt(13)
	s_branch .Ltl2_w
.Ltl2_ns:
	s_waitcnt vmcnt(5)
.Ltl2_w:
	v_mfma_f32_16x16x32_bf16 v[60:63], v[204:207], v[208:211], v[60:63]
	v_mfma_f32_16x16x32_bf16 v[56:59], v[204:207], v[224:227], v[56:59]
	v_mfma_f32_16x16x32_bf16 v[44:47], v[204:207], v[240:243], v[44:47]
	v_mfma_f32_16x16x32_bf16 v[40:43], v[204:207], v[248:251], v[40:43]
	v_mfma_f32_16x16x32_bf16 v[28:31], v[212:215], v[208:211], v[28:31]
	v_mfma_f32_16x16x32_bf16 v[24:27], v[212:215], v[224:227], v[24:27]
	v_mfma_f32_16x16x32_bf16 v[12:15], v[212:215], v[240:243], v[12:15]
	v_mfma_f32_16x16x32_bf16 v[8:11], v[212:215], v[248:251], v[8:11]
	v_mfma_f32_16x16x32_bf16 v[48:51], v[236:239], v[208:211], v[48:51]
	v_mfma_f32_16x16x32_bf16 v[52:55], v[236:239], v[224:227], v[52:55]
	v_mfma_f32_16x16x32_bf16 v[32:35], v[236:239], v[240:243], v[32:35]
	v_mfma_f32_16x16x32_bf16 v[36:39], v[236:239], v[248:251], v[36:39]
	v_mfma_f32_16x16x32_bf16 v[16:19], v[244:247], v[208:211], v[16:19]
	v_mfma_f32_16x16x32_bf16 v[20:23], v[244:247], v[224:227], v[20:23]
	v_mfma_f32_16x16x32_bf16 v[0:3], v[244:247], v[240:243], v[0:3]
	v_mfma_f32_16x16x32_bf16 v[4:7], v[244:247], v[248:251], v[4:7]
	v_mov_b32_e32 v225, v80
	v_mov_b32_e32 v82, v81
	v_mov_b32_e32 v83, v81
.LBB0_1528:
	s_or_b64 exec, exec, s[4:5]
	ds_write2_b32 v181, v60, v56 offset1:16
	ds_write2_b32 v181, v61, v57 offset0:65 offset1:81
	ds_write2_b32 v181, v62, v58 offset0:130 offset1:146
	ds_write2_b32 v181, v63, v59 offset0:195 offset1:211
	ds_write2_b32 v181, v44, v40 offset0:32 offset1:48
	ds_write2_b32 v181, v45, v41 offset0:97 offset1:113
	ds_write2_b32 v181, v46, v42 offset0:162 offset1:178
	ds_write2_b32 v181, v47, v43 offset0:227 offset1:243
	v_add_u32_e32 v40, 0x1000, v181
	ds_write2_b32 v40, v28, v24 offset0:16 offset1:32
	ds_write2_b32 v40, v29, v25 offset0:81 offset1:97
	ds_write2_b32 v40, v30, v26 offset0:146 offset1:162
	ds_write2_b32 v40, v31, v27 offset0:211 offset1:227
	ds_write2_b32 v40, v12, v8 offset0:48 offset1:64
	ds_write2_b32 v40, v13, v9 offset0:113 offset1:129
	ds_write2_b32 v40, v14, v10 offset0:178 offset1:194
	v_add_u32_e32 v8, 0x1200, v181
	ds_write2_b32 v8, v15, v11 offset0:115 offset1:131
	v_add_u32_e32 v8, 0x2000, v181
	ds_write2_b32 v8, v48, v52 offset0:32 offset1:48
	ds_write2_b32 v8, v49, v53 offset0:97 offset1:113
	ds_write2_b32 v8, v50, v54 offset0:162 offset1:178
	ds_write2_b32 v8, v51, v55 offset0:227 offset1:243
	ds_write2_b32 v8, v32, v36 offset0:64 offset1:80
	ds_write2_b32 v8, v33, v37 offset0:129 offset1:145
	ds_write2_b32 v8, v34, v38 offset0:194 offset1:210
	v_add_u32_e32 v8, 0x2400, v181
	ds_write2_b32 v8, v35, v39 offset0:3 offset1:19
	v_add_u32_e32 v8, 0x3000, v181
	v_add_u32_e32 v9, 0x3200, v181
	ds_write2_b32 v8, v16, v20 offset0:48 offset1:64
	ds_write2_b32 v8, v17, v21 offset0:113 offset1:129
	ds_write2_b32 v8, v18, v22 offset0:178 offset1:194
	ds_write2_b32 v9, v19, v23 offset0:115 offset1:131
	ds_write2_b32 v8, v0, v4 offset0:80 offset1:96
	ds_write2_b32 v8, v1, v5 offset0:145 offset1:161
	ds_write2_b32 v8, v2, v6 offset0:210 offset1:226
	v_add_u32_e32 v0, 0x3400, v181
	v_add_u32_e32 v2, s1, v178
	ds_write2_b32 v0, v3, v7 offset0:19 offset1:35
	v_ashrrev_i32_e32 v3, 31, v2
	s_waitcnt vmcnt(5)
	v_or_b32_e32 v77, s0, v179
	v_lshlrev_b64 v[0:1], 11, v[2:3]
	v_lshl_add_u64 v[0:1], s[20:21], 0, v[0:1]
	v_lshlrev_b32_e32 v80, 1, v77
	s_waitcnt lgkmcnt(0)
	s_barrier
; __device__ __forceinline__ float bflo(unsigned w) { return __uint_as_float(w << 16); }
; __device__ __forceinline__ float bfhi(unsigned w) { return __uint_as_float(w & 0xffff0000u); }
; template <int EPI> __device__ __forceinline__ void tail_gemm(LAS unsigned char* lds, const bf16* Am, const bf16* Bt, int K, const TailEpi& E, int tid_in) {
;     ...
;     } else {
;         const u32x4 zw = *(const u32x4*)(E.ZB + off);
;         f32x4 x0 = {bflo(zw.x), bfhi(zw.x), bflo(zw.y), bfhi(zw.y)}, x1 = {bflo(zw.z), bfhi(zw.z), bflo(zw.w), bfhi(zw.w)};
;         if (E.pst) {
;             const f32x4* sp = (const f32x4*)(E.pst + (size_t)row * 32); float s = 0.f, q = 0.f;
; #pragma unroll
;             for (int i = 0; i < 8; ++i) { const f32x4 t = sp[i]; s += t[0] + t[2]; q += t[1] + t[3]; }
;             const float mu = s * (1.f / D), rstd = __builtin_amdgcn_rsqf(fmaxf(q * (1.f / D) - mu * mu, 0.f) + LN_EPS);
;             const f32x4 g0 = *(const f32x4*)(E.pg + col), g1 = *(const f32x4*)(E.pg + col + 4), b0 = *(const f32x4*)(E.pb + col), b1 = *(const f32x4*)(E.pb + col + 4);
;             x0 = (x0 - mu) * rstd * g0 + b0; x1 = (x1 - mu) * rstd * g1 + b1;
;         }
;         x0 = x0 * ALPHA + v0; x1 = x1 * ALPHA + v1;
;         if (E.Z) { *(f32x4*)(E.Z + off) = x0; *(f32x4*)(E.Z + off + 4) = x1; }
	v_lshl_add_u64 v[0:1], v[0:1], 0, v[80:81]
	s_waitcnt vmcnt(0)
	v_mov_b32_e32 v72, v100
	v_mov_b32_e32 v73, v101
	v_mov_b32_e32 v74, v102
	v_mov_b32_e32 v75, v103
	v_add_u32_e32 v4, 0x4100, v180
	v_add_u32_e32 v5, 0x8200, v180
	v_add_u32_e32 v6, 0xc300, v180
	v_add_u32_e32 v7, 0x4108, v180
	ds_read2_b32 v[12:13], v4 offset1:1
	ds_read2_b32 v[8:9], v5 offset1:1
	ds_read2_b32 v[10:11], v6 offset1:1
	ds_read2_b32 v[18:19], v7 offset1:1
	v_add_u32_e32 v4, 0x8208, v180
	v_add_u32_e32 v5, 0xc308, v180
	v_add_u32_e32 v6, 0x4110, v180
	v_add_u32_e32 v14, 0x8210, v180
	v_add_u32_e32 v16, 0xc310, v180
	v_add_u32_e32 v22, 0x4118, v180
	v_add_u32_e32 v23, 0x8218, v180
	v_add_u32_e32 v24, 0xc318, v180
	ds_read2_b32 v[34:35], v4 offset1:1
	ds_read2_b32 v[26:27], v5 offset1:1
	ds_read2_b32 v[6:7], v6 offset1:1
	ds_read2_b32 v[4:5], v14 offset1:1
	ds_read2_b32 v[50:51], v180 offset1:1
	ds_read2_b32 v[54:55], v180 offset0:2 offset1:3
	ds_read2_b32 v[14:15], v180 offset0:4 offset1:5
	ds_read2_b32 v[20:21], v180 offset0:6 offset1:7
	ds_read2_b32 v[16:17], v16 offset1:1
	ds_read2_b32 v[28:29], v22 offset1:1
	ds_read2_b32 v[30:31], v23 offset1:1
	ds_read2_b32 v[22:23], v24 offset1:1
	ds_read2_b32 v[56:57], v182 offset1:1
	ds_read2_b32 v[58:59], v183 offset1:1
	ds_read2_b32 v[24:25], v184 offset1:1
	ds_read2_b32 v[32:33], v185 offset1:1
	ds_read2_b32 v[60:61], v190 offset1:1
	ds_read2_b32 v[62:63], v191 offset1:1
	ds_read2_b32 v[36:37], v192 offset1:1
	ds_read2_b32 v[38:39], v193 offset1:1
	ds_read2_b32 v[64:65], v194 offset1:1
	ds_read2_b32 v[66:67], v195 offset1:1
	ds_read2_b32 v[40:41], v196 offset1:1
	ds_read2_b32 v[42:43], v197 offset1:1
	ds_read2_b32 v[68:69], v198 offset1:1
	ds_read2_b32 v[70:71], v199 offset1:1
	ds_read2_b32 v[44:45], v200 offset1:1
	ds_read2_b32 v[46:47], v201 offset1:1
	s_and_b64 vcc, exec, s[2:3]
	v_lshlrev_b64 v[2:3], 7, v[2:3]
	s_waitcnt vmcnt(0)
	v_lshlrev_b32_e32 v48, 16, v72
	v_and_b32_e32 v49, 0xffff0000, v72
	v_lshlrev_b32_e32 v52, 16, v73
	v_and_b32_e32 v53, 0xffff0000, v73
	v_lshlrev_b32_e32 v72, 16, v74
	v_and_b32_e32 v73, 0xffff0000, v74
	v_lshlrev_b32_e32 v74, 16, v75
	v_and_b32_e32 v75, 0xffff0000, v75
	s_cbranch_vccz .LBB0_1530
	v_lshl_add_u64 v[78:79], s[46:47], 0, v[2:3]
	s_waitcnt vmcnt(0)
	v_mov_b32_e32 v82, v104
	v_mov_b32_e32 v83, v105
	v_mov_b32_e32 v84, v106
	v_mov_b32_e32 v85, v107
	s_waitcnt vmcnt(0)
	v_mov_b32_e32 v86, v108
	v_mov_b32_e32 v87, v109
	v_mov_b32_e32 v88, v110
	v_mov_b32_e32 v89, v111
	s_waitcnt vmcnt(0)
	v_mov_b32_e32 v90, v112
	v_mov_b32_e32 v91, v113
	v_mov_b32_e32 v92, v114
	v_mov_b32_e32 v93, v115
	s_waitcnt vmcnt(0)
	v_mov_b32_e32 v94, v116
	v_mov_b32_e32 v95, v117
	v_mov_b32_e32 v96, v118
	v_mov_b32_e32 v97, v119
	s_waitcnt vmcnt(0)
	v_mov_b32_e32 v98, v120
	v_mov_b32_e32 v99, v121
	v_mov_b32_e32 v100, v122
	v_mov_b32_e32 v101, v123
	s_waitcnt vmcnt(0)
	v_mov_b32_e32 v102, v124
	v_mov_b32_e32 v103, v125
	v_mov_b32_e32 v104, v126
	v_mov_b32_e32 v105, v127
	s_waitcnt vmcnt(0)
	v_mov_b32_e32 v106, v128
	v_mov_b32_e32 v107, v129
	v_mov_b32_e32 v108, v130
	v_mov_b32_e32 v109, v131
	s_waitcnt vmcnt(0)
	v_mov_b32_e32 v110, v132
	v_mov_b32_e32 v111, v133
	v_mov_b32_e32 v112, v134
	v_mov_b32_e32 v113, v135
	v_lshlrev_b32_e32 v77, 2, v77
	s_mov_b32 s0, 0x3a800000
	s_waitcnt vmcnt(7)
	v_pk_add_f32 v[82:83], v[82:83], v[84:85]
	s_waitcnt vmcnt(6)
	v_pk_add_f32 v[86:87], v[86:87], v[88:89]
	s_waitcnt vmcnt(5)
	v_pk_add_f32 v[90:91], v[90:91], v[92:93]
	s_waitcnt vmcnt(4)
	v_pk_add_f32 v[78:79], v[94:95], v[96:97]
	s_nop 0
	v_pk_add_f32 v[78:79], v[78:79], 0 op_sel_hi:[1,0]
	s_nop 0
	v_pk_add_f32 v[78:79], v[78:79], v[90:91]
	s_nop 0
	v_pk_add_f32 v[78:79], v[78:79], v[86:87]
	s_nop 0
	v_pk_add_f32 v[78:79], v[78:79], v[82:83]
	s_waitcnt vmcnt(0)
	v_pk_add_f32 v[82:83], v[110:111], v[112:113]
	s_nop 0
	v_pk_add_f32 v[78:79], v[78:79], v[82:83]
	v_pk_add_f32 v[82:83], v[106:107], v[108:109]
	s_nop 0
	v_pk_add_f32 v[78:79], v[78:79], v[82:83]
	v_pk_add_f32 v[82:83], v[102:103], v[104:105]
	s_nop 0
	v_pk_add_f32 v[78:79], v[78:79], v[82:83]
	v_pk_add_f32 v[82:83], v[98:99], v[100:101]
	s_nop 0
	v_pk_add_f32 v[78:79], v[78:79], v[82:83]
	s_waitcnt vmcnt(0)
	v_mov_b32_e32 v82, v136
	v_mov_b32_e32 v83, v137
	v_mov_b32_e32 v84, v138
	v_mov_b32_e32 v85, v139
	s_waitcnt vmcnt(0)
	v_mov_b32_e32 v86, v140
	v_mov_b32_e32 v87, v141
	v_mov_b32_e32 v88, v142
	v_mov_b32_e32 v89, v143
	s_waitcnt vmcnt(0)
	v_mov_b32_e32 v90, v144
	v_mov_b32_e32 v91, v145
	v_mov_b32_e32 v92, v146
	v_mov_b32_e32 v93, v147
	s_waitcnt vmcnt(0)
	v_mov_b32_e32 v94, v148
	v_mov_b32_e32 v95, v149
	v_mov_b32_e32 v96, v150
	v_mov_b32_e32 v97, v151
	v_pk_mul_f32 v[78:79], v[78:79], s[0:1] op_sel_hi:[1,0]
	s_nop 0
	v_fma_f32 v76, -v78, v78, v79
	v_max_f32_e32 v76, 0, v76
	v_add_f32_e32 v76, 0x3727c5ac, v76
	v_rsq_f32_e32 v76, v76
	v_sub_f32_e32 v53, v53, v78
	v_sub_f32_e32 v52, v52, v78
	v_sub_f32_e32 v49, v49, v78
	v_sub_f32_e32 v48, v48, v78
	v_sub_f32_e32 v75, v75, v78
	v_sub_f32_e32 v74, v74, v78
	v_sub_f32_e32 v73, v73, v78
	v_sub_f32_e32 v72, v72, v78
	v_pk_mul_f32 v[48:49], v[48:49], v[76:77] op_sel_hi:[1,0]
	v_pk_mul_f32 v[52:53], v[52:53], v[76:77] op_sel_hi:[1,0]
	v_pk_mul_f32 v[72:73], v[72:73], v[76:77] op_sel_hi:[1,0]
	v_pk_mul_f32 v[74:75], v[74:75], v[76:77] op_sel_hi:[1,0]
	s_waitcnt vmcnt(1)
	v_pk_fma_f32 v[72:73], v[82:83], v[72:73], v[90:91]
	s_waitcnt vmcnt(0)
	v_pk_fma_f32 v[52:53], v[88:89], v[52:53], v[96:97]
	v_pk_fma_f32 v[48:49], v[86:87], v[48:49], v[94:95]
	v_pk_fma_f32 v[74:75], v[84:85], v[74:75], v[92:93]

; #define TG_LOAD(A_, B_, KS_) do { const int ks_ = (KS_) < nks ? (KS_) : w; _Pragma("unroll") for (int i = 0; i < 4; ++i) { A_[i] = *(const bf16x8*)(ap + (size_t)i * 16 * K + ks_ * 32); B_[i] = *(const bf16x8*)(bp + (size_t)i * 16 * K + ks_ * 32); } } while (0)
; template <int EPI> __device__ __forceinline__ void tail_gemm(LAS unsigned char* lds, const bf16* Am, const bf16* Bt, int K, const TailEpi& E, int tid_in) {
;     ...
;     const int tid = tid_in, lane = tid & 63, w = tid >> 6, l15 = lane & 15, q4 = lane >> 4;
;     const int row0 = MAIN_ROWS + (su >> 4) * 64, col0 = (su & 15) * 64;
;     f32x4 acc[4][4];
; #pragma unroll
;     for (int i = 0; i < 4; ++i)
; #pragma unroll
;         for (int j = 0; j < 4; ++j) acc[i][j] = (f32x4){0.f, 0.f, 0.f, 0.f};
;     const bf16* ap = Am + (size_t)(row0 + l15) * K + q4 * 8;
;     const bf16* bp = Bt + (size_t)(col0 + l15) * K + q4 * 8;
;     {
;         const int nks = K / 32;
;         bf16x8 a0[4], b0[4], a1[4], b1[4], a2[4], b2[4];
;     ...
;         TG_LOAD(a0, b0, w); TG_LOAD(a1, b1, w + 8);
;         for (int ks = w; ks < nks; ks += 24) {
.LBB0_1753:
	s_lshl_b32 s0, s12, 2
	v_mov_b32_e32 v80, v81
	s_and_b32 s1, s0, 0xffffffc0
	s_and_b32 s13, s12, 15
	v_mov_b32_e32 v82, v81
	v_mov_b32_e32 v83, v81
	v_mov_b64_e32 v[4:5], v[80:81]
	s_waitcnt lgkmcnt(0)
	v_mov_b64_e32 v[0:1], v[80:81]
	v_mov_b64_e32 v[20:21], v[80:81]
	v_mov_b64_e32 v[16:17], v[80:81]
	v_mov_b64_e32 v[36:37], v[80:81]
	v_mov_b64_e32 v[32:33], v[80:81]
	v_mov_b64_e32 v[52:53], v[80:81]
	v_mov_b64_e32 v[48:49], v[80:81]
	v_mov_b64_e32 v[60:61], v[80:81]
	v_mov_b64_e32 v[56:57], v[80:81]
	s_waitcnt vmcnt(0)
	v_mov_b64_e32 v[44:45], v[80:81]
	v_mov_b64_e32 v[40:41], v[80:81]
	v_mov_b64_e32 v[28:29], v[80:81]
	v_mov_b64_e32 v[24:25], v[80:81]
	v_mov_b64_e32 v[12:13], v[80:81]
	v_mov_b64_e32 v[8:9], v[80:81]
	s_addk_i32 s1, 0x4000
	s_lshl_b32 s0, s13, 6
	v_mov_b64_e32 v[6:7], v[82:83]
	v_mov_b64_e32 v[2:3], v[82:83]
	v_mov_b64_e32 v[22:23], v[82:83]
	v_mov_b64_e32 v[18:19], v[82:83]
	v_mov_b64_e32 v[38:39], v[82:83]
	v_mov_b64_e32 v[34:35], v[82:83]
	v_mov_b64_e32 v[54:55], v[82:83]
	v_mov_b64_e32 v[50:51], v[82:83]
	v_mov_b64_e32 v[62:63], v[82:83]
	v_mov_b64_e32 v[58:59], v[82:83]
	v_mov_b64_e32 v[46:47], v[82:83]
	v_mov_b64_e32 v[42:43], v[82:83]
	v_mov_b64_e32 v[30:31], v[82:83]
	v_mov_b64_e32 v[26:27], v[82:83]
	v_mov_b64_e32 v[14:15], v[82:83]
	v_mov_b64_e32 v[10:11], v[82:83]
	s_and_saveexec_b64 s[2:3], s[36:37]
	s_cbranch_execz .LBB0_1761
	v_or_b32_e32 v0, s1, v177
	v_mad_i64_i32 v[172:173], s[4:5], v0, s92, v[164:165]
	v_or_b32_e32 v0, s0, v177
	v_mul_u32_u24_e32 v0, 0xb00, v0
	v_lshlrev_b32_e32 v80, 1, v0
	v_lshl_add_u64 v[174:175], v[166:167], 0, v[80:81]
	v_lshlrev_b32_e32 v80, 6, v176
	v_lshl_add_u64 v[172:173], v[172:173], 0, v[80:81]
	v_lshl_add_u64 v[174:175], v[174:175], 0, v[80:81]
	s_mov_b64 s[40:41], 0x16000
	v_mov_b32_e32 v80, v225
	v_lshl_add_u64 v[186:187], v[172:173], 0, s[40:41]
	v_lshl_add_u64 v[188:189], v[174:175], 0, s[40:41]
	v_lshl_add_u64 v[202:203], v[186:187], 0, s[40:41]
	v_lshl_add_u64 v[228:229], v[188:189], 0, s[40:41]
	v_lshl_add_u64 v[234:235], v[202:203], 0, s[40:41]
	v_lshl_add_u64 v[82:83], v[228:229], 0, s[40:41]
	global_load_dwordx4 v[64:67], v[172:173], off
	global_load_dwordx4 v[68:71], v[174:175], off
	global_load_dwordx4 v[72:75], v[186:187], off
	global_load_dwordx4 v[76:79], v[188:189], off
	global_load_dwordx4 v[84:87], v[202:203], off
	global_load_dwordx4 v[88:91], v[228:229], off
	global_load_dwordx4 v[92:95], v[234:235], off
	global_load_dwordx4 v[96:99], v[82:83], off
	global_load_dwordx4 v[100:103], v[172:173], off offset:512
	global_load_dwordx4 v[104:107], v[174:175], off offset:512
	global_load_dwordx4 v[108:111], v[186:187], off offset:512
	global_load_dwordx4 v[112:115], v[188:189], off offset:512
	global_load_dwordx4 v[116:119], v[202:203], off offset:512
	global_load_dwordx4 v[120:123], v[228:229], off offset:512
	global_load_dwordx4 v[124:127], v[234:235], off offset:512
	global_load_dwordx4 v[128:131], v[82:83], off offset:512
	global_load_dwordx4 v[132:135], v[172:173], off offset:1024
	global_load_dwordx4 v[136:139], v[174:175], off offset:1024
	global_load_dwordx4 v[140:143], v[186:187], off offset:1024
	global_load_dwordx4 v[144:147], v[188:189], off offset:1024
	global_load_dwordx4 v[148:151], v[202:203], off offset:1024
	global_load_dwordx4 v[152:155], v[228:229], off offset:1024
	global_load_dwordx4 v[156:159], v[234:235], off offset:1024
	global_load_dwordx4 v[160:163], v[82:83], off offset:1024
	global_load_dwordx4 v[204:207], v[172:173], off offset:1536
	global_load_dwordx4 v[208:211], v[174:175], off offset:1536
	global_load_dwordx4 v[212:215], v[186:187], off offset:1536
	global_load_dwordx4 v[224:227], v[188:189], off offset:1536
	global_load_dwordx4 v[236:239], v[202:203], off offset:1536
	global_load_dwordx4 v[240:243], v[228:229], off offset:1536
	global_load_dwordx4 v[244:247], v[234:235], off offset:1536
	global_load_dwordx4 v[248:251], v[82:83], off offset:1536
	s_waitcnt vmcnt(24)
	v_mfma_f32_16x16x32_bf16 v[60:63], v[64:67], v[68:71], v[60:63]
	v_mfma_f32_16x16x32_bf16 v[56:59], v[64:67], v[76:79], v[56:59]
	v_mfma_f32_16x16x32_bf16 v[44:47], v[64:67], v[88:91], v[44:47]
	v_mfma_f32_16x16x32_bf16 v[40:43], v[64:67], v[96:99], v[40:43]
	v_mfma_f32_16x16x32_bf16 v[28:31], v[72:75], v[68:71], v[28:31]
	v_mfma_f32_16x16x32_bf16 v[24:27], v[72:75], v[76:79], v[24:27]
	v_mfma_f32_16x16x32_bf16 v[12:15], v[72:75], v[88:91], v[12:15]
	v_mfma_f32_16x16x32_bf16 v[8:11], v[72:75], v[96:99], v[8:11]
	v_mfma_f32_16x16x32_bf16 v[48:51], v[84:87], v[68:71], v[48:51]
	v_mfma_f32_16x16x32_bf16 v[52:55], v[84:87], v[76:79], v[52:55]
	v_mfma_f32_16x16x32_bf16 v[32:35], v[84:87], v[88:91], v[32:35]
	v_mfma_f32_16x16x32_bf16 v[36:39], v[84:87], v[96:99], v[36:39]
	v_mfma_f32_16x16x32_bf16 v[16:19], v[92:95], v[68:71], v[16:19]
	v_mfma_f32_16x16x32_bf16 v[20:23], v[92:95], v[76:79], v[20:23]
	v_mfma_f32_16x16x32_bf16 v[0:3], v[92:95], v[88:91], v[0:3]
	v_mfma_f32_16x16x32_bf16 v[4:7], v[92:95], v[96:99], v[4:7]
	global_load_dwordx4 v[64:67], v[172:173], off offset:2048
	global_load_dwordx4 v[68:71], v[174:175], off offset:2048
	global_load_dwordx4 v[72:75], v[186:187], off offset:2048
	global_load_dwordx4 v[76:79], v[188:189], off offset:2048
	global_load_dwordx4 v[84:87], v[202:203], off offset:2048
	global_load_dwordx4 v[88:91], v[228:229], off offset:2048
	global_load_dwordx4 v[92:95], v[234:235], off offset:2048
	global_load_dwordx4 v[96:99], v[82:83], off offset:2048
	s_waitcnt vmcnt(24)
; #define TG_LOAD(A_, B_, KS_) do { const int ks_ = (KS_) < nks ? (KS_) : w; _Pragma("unroll") for (int i = 0; i < 4; ++i) { A_[i] = *(const bf16x8*)(ap + (size_t)i * 16 * K + ks_ * 32); B_[i] = *(const bf16x8*)(bp + (size_t)i * 16 * K + ks_ * 32); } } while (0)
; #define TG_MMA(A_, B_) do { _Pragma("unroll") for (int i = 0; i < 4; ++i) _Pragma("unroll") for (int j = 0; j < 4; ++j) acc[i][j] = __builtin_amdgcn_mfma_f32_16x16x32_bf16(A_[i], B_[j], acc[i][j], 0, 0, 0); } while (0)
; template <int EPI> __device__ __forceinline__ void tail_gemm(LAS unsigned char* lds, const bf16* Am, const bf16* Bt, int K, const TailEpi& E, int tid_in) {
;     ...
;         for (int ks = w; ks < nks; ks += 24) {
;             TG_LOAD(a2, b2, ks + 16); TG_MMA(a0, b0);
;             if (ks + 8 < nks) { TG_LOAD(a0, b0, ks + 24); TG_MMA(a1, b1); }
;             if (ks + 16 < nks) { TG_LOAD(a1, b1, ks + 32); TG_MMA(a2, b2); }
;         }
	v_mfma_f32_16x16x32_bf16 v[60:63], v[100:103], v[104:107], v[60:63]
	v_mfma_f32_16x16x32_bf16 v[56:59], v[100:103], v[112:115], v[56:59]
	v_mfma_f32_16x16x32_bf16 v[44:47], v[100:103], v[120:123], v[44:47]
	v_mfma_f32_16x16x32_bf16 v[40:43], v[100:103], v[128:131], v[40:43]
	v_mfma_f32_16x16x32_bf16 v[28:31], v[108:111], v[104:107], v[28:31]
	v_mfma_f32_16x16x32_bf16 v[24:27], v[108:111], v[112:115], v[24:27]
	v_mfma_f32_16x16x32_bf16 v[12:15], v[108:111], v[120:123], v[12:15]
	v_mfma_f32_16x16x32_bf16 v[8:11], v[108:111], v[128:131], v[8:11]
	v_mfma_f32_16x16x32_bf16 v[48:51], v[116:119], v[104:107], v[48:51]
	v_mfma_f32_16x16x32_bf16 v[52:55], v[116:119], v[112:115], v[52:55]
	v_mfma_f32_16x16x32_bf16 v[32:35], v[116:119], v[120:123], v[32:35]
	v_mfma_f32_16x16x32_bf16 v[36:39], v[116:119], v[128:131], v[36:39]
	v_mfma_f32_16x16x32_bf16 v[16:19], v[124:127], v[104:107], v[16:19]
	v_mfma_f32_16x16x32_bf16 v[20:23], v[124:127], v[112:115], v[20:23]
	v_mfma_f32_16x16x32_bf16 v[0:3], v[124:127], v[120:123], v[0:3]
	v_mfma_f32_16x16x32_bf16 v[4:7], v[124:127], v[128:131], v[4:7]
	global_load_dwordx4 v[100:103], v[172:173], off offset:2560
	global_load_dwordx4 v[104:107], v[174:175], off offset:2560
	global_load_dwordx4 v[108:111], v[186:187], off offset:2560
	global_load_dwordx4 v[112:115], v[188:189], off offset:2560
	global_load_dwordx4 v[116:119], v[202:203], off offset:2560
	global_load_dwordx4 v[120:123], v[228:229], off offset:2560
	global_load_dwordx4 v[124:127], v[234:235], off offset:2560
	global_load_dwordx4 v[128:131], v[82:83], off offset:2560
	s_waitcnt vmcnt(24)
	v_mfma_f32_16x16x32_bf16 v[60:63], v[132:135], v[136:139], v[60:63]
	v_mfma_f32_16x16x32_bf16 v[56:59], v[132:135], v[144:147], v[56:59]
	v_mfma_f32_16x16x32_bf16 v[44:47], v[132:135], v[152:155], v[44:47]
	v_mfma_f32_16x16x32_bf16 v[40:43], v[132:135], v[160:163], v[40:43]
	v_mfma_f32_16x16x32_bf16 v[28:31], v[140:143], v[136:139], v[28:31]
	v_mfma_f32_16x16x32_bf16 v[24:27], v[140:143], v[144:147], v[24:27]
	v_mfma_f32_16x16x32_bf16 v[12:15], v[140:143], v[152:155], v[12:15]
	v_mfma_f32_16x16x32_bf16 v[8:11], v[140:143], v[160:163], v[8:11]
	v_mfma_f32_16x16x32_bf16 v[48:51], v[148:151], v[136:139], v[48:51]
	v_mfma_f32_16x16x32_bf16 v[52:55], v[148:151], v[144:147], v[52:55]
	v_mfma_f32_16x16x32_bf16 v[32:35], v[148:151], v[152:155], v[32:35]
	v_mfma_f32_16x16x32_bf16 v[36:39], v[148:151], v[160:163], v[36:39]
	v_mfma_f32_16x16x32_bf16 v[16:19], v[156:159], v[136:139], v[16:19]
	v_mfma_f32_16x16x32_bf16 v[20:23], v[156:159], v[144:147], v[20:23]
	v_mfma_f32_16x16x32_bf16 v[0:3], v[156:159], v[152:155], v[0:3]
	v_mfma_f32_16x16x32_bf16 v[4:7], v[156:159], v[160:163], v[4:7]
	global_load_dwordx4 v[132:135], v[172:173], off offset:3072
	global_load_dwordx4 v[136:139], v[174:175], off offset:3072
	global_load_dwordx4 v[140:143], v[186:187], off offset:3072
	global_load_dwordx4 v[144:147], v[188:189], off offset:3072
	global_load_dwordx4 v[148:151], v[202:203], off offset:3072
	global_load_dwordx4 v[152:155], v[228:229], off offset:3072
	global_load_dwordx4 v[156:159], v[234:235], off offset:3072
	global_load_dwordx4 v[160:163], v[82:83], off offset:3072
	s_waitcnt vmcnt(24)
	v_mfma_f32_16x16x32_bf16 v[60:63], v[204:207], v[208:211], v[60:63]
	v_mfma_f32_16x16x32_bf16 v[56:59], v[204:207], v[224:227], v[56:59]
	v_mfma_f32_16x16x32_bf16 v[44:47], v[204:207], v[240:243], v[44:47]
	v_mfma_f32_16x16x32_bf16 v[40:43], v[204:207], v[248:251], v[40:43]
	v_mfma_f32_16x16x32_bf16 v[28:31], v[212:215], v[208:211], v[28:31]
	v_mfma_f32_16x16x32_bf16 v[24:27], v[212:215], v[224:227], v[24:27]
	v_mfma_f32_16x16x32_bf16 v[12:15], v[212:215], v[240:243], v[12:15]
	v_mfma_f32_16x16x32_bf16 v[8:11], v[212:215], v[248:251], v[8:11]
	v_mfma_f32_16x16x32_bf16 v[48:51], v[236:239], v[208:211], v[48:51]
	v_mfma_f32_16x16x32_bf16 v[52:55], v[236:239], v[224:227], v[52:55]
	v_mfma_f32_16x16x32_bf16 v[32:35], v[236:239], v[240:243], v[32:35]
	v_mfma_f32_16x16x32_bf16 v[36:39], v[236:239], v[248:251], v[36:39]
	v_mfma_f32_16x16x32_bf16 v[16:19], v[244:247], v[208:211], v[16:19]
	v_mfma_f32_16x16x32_bf16 v[20:23], v[244:247], v[224:227], v[20:23]
	v_mfma_f32_16x16x32_bf16 v[0:3], v[244:247], v[240:243], v[0:3]
	v_mfma_f32_16x16x32_bf16 v[4:7], v[244:247], v[248:251], v[4:7]
	global_load_dwordx4 v[204:207], v[172:173], off offset:3584
	global_load_dwordx4 v[208:211], v[174:175], off offset:3584
	global_load_dwordx4 v[212:215], v[186:187], off offset:3584
	global_load_dwordx4 v[224:227], v[188:189], off offset:3584
	global_load_dwordx4 v[236:239], v[202:203], off offset:3584
	global_load_dwordx4 v[240:243], v[228:229], off offset:3584
	global_load_dwordx4 v[244:247], v[234:235], off offset:3584
	global_load_dwordx4 v[248:251], v[82:83], off offset:3584
	s_waitcnt vmcnt(24)
; #define TG_LOAD(A_, B_, KS_) do { const int ks_ = (KS_) < nks ? (KS_) : w; _Pragma("unroll") for (int i = 0; i < 4; ++i) { A_[i] = *(const bf16x8*)(ap + (size_t)i * 16 * K + ks_ * 32); B_[i] = *(const bf16x8*)(bp + (size_t)i * 16 * K + ks_ * 32); } } while (0)
; #define TG_MMA(A_, B_) do { _Pragma("unroll") for (int i = 0; i < 4; ++i) _Pragma("unroll") for (int j = 0; j < 4; ++j) acc[i][j] = __builtin_amdgcn_mfma_f32_16x16x32_bf16(A_[i], B_[j], acc[i][j], 0, 0, 0); } while (0)
; template <int EPI> __device__ __forceinline__ void tail_gemm(LAS unsigned char* lds, const bf16* Am, const bf16* Bt, int K, const TailEpi& E, int tid_in) {
;     ...
;         for (int ks = w; ks < nks; ks += 24) {
;             TG_LOAD(a2, b2, ks + 16); TG_MMA(a0, b0);
;             if (ks + 8 < nks) { TG_LOAD(a0, b0, ks + 24); TG_MMA(a1, b1); }
;             if (ks + 16 < nks) { TG_LOAD(a1, b1, ks + 32); TG_MMA(a2, b2); }
;         }
	v_mfma_f32_16x16x32_bf16 v[60:63], v[64:67], v[68:71], v[60:63]
	v_mfma_f32_16x16x32_bf16 v[56:59], v[64:67], v[76:79], v[56:59]
	v_mfma_f32_16x16x32_bf16 v[44:47], v[64:67], v[88:91], v[44:47]
	v_mfma_f32_16x16x32_bf16 v[40:43], v[64:67], v[96:99], v[40:43]
	v_mfma_f32_16x16x32_bf16 v[28:31], v[72:75], v[68:71], v[28:31]
	v_mfma_f32_16x16x32_bf16 v[24:27], v[72:75], v[76:79], v[24:27]
	v_mfma_f32_16x16x32_bf16 v[12:15], v[72:75], v[88:91], v[12:15]
	v_mfma_f32_16x16x32_bf16 v[8:11], v[72:75], v[96:99], v[8:11]
	v_mfma_f32_16x16x32_bf16 v[48:51], v[84:87], v[68:71], v[48:51]
	v_mfma_f32_16x16x32_bf16 v[52:55], v[84:87], v[76:79], v[52:55]
	v_mfma_f32_16x16x32_bf16 v[32:35], v[84:87], v[88:91], v[32:35]
	v_mfma_f32_16x16x32_bf16 v[36:39], v[84:87], v[96:99], v[36:39]
	v_mfma_f32_16x16x32_bf16 v[16:19], v[92:95], v[68:71], v[16:19]
	v_mfma_f32_16x16x32_bf16 v[20:23], v[92:95], v[76:79], v[20:23]
	v_mfma_f32_16x16x32_bf16 v[0:3], v[92:95], v[88:91], v[0:3]
	v_mfma_f32_16x16x32_bf16 v[4:7], v[92:95], v[96:99], v[4:7]
	s_mov_b64 s[40:41], 0x1000
	v_lshl_add_u64 v[172:173], v[172:173], 0, s[40:41]
	v_lshl_add_u64 v[174:175], v[174:175], 0, s[40:41]
	v_lshl_add_u64 v[186:187], v[186:187], 0, s[40:41]
	v_lshl_add_u64 v[188:189], v[188:189], 0, s[40:41]
	v_lshl_add_u64 v[202:203], v[202:203], 0, s[40:41]
	v_lshl_add_u64 v[228:229], v[228:229], 0, s[40:41]
	v_lshl_add_u64 v[234:235], v[234:235], 0, s[40:41]
	v_lshl_add_u64 v[82:83], v[82:83], 0, s[40:41]
	global_load_dwordx4 v[64:67], v[172:173], off
	global_load_dwordx4 v[68:71], v[174:175], off
	global_load_dwordx4 v[72:75], v[186:187], off
	global_load_dwordx4 v[76:79], v[188:189], off
	global_load_dwordx4 v[84:87], v[202:203], off
	global_load_dwordx4 v[88:91], v[228:229], off
	global_load_dwordx4 v[92:95], v[234:235], off
	global_load_dwordx4 v[96:99], v[82:83], off
	s_waitcnt vmcnt(24)
	v_mfma_f32_16x16x32_bf16 v[60:63], v[100:103], v[104:107], v[60:63]
	v_mfma_f32_16x16x32_bf16 v[56:59], v[100:103], v[112:115], v[56:59]
	v_mfma_f32_16x16x32_bf16 v[44:47], v[100:103], v[120:123], v[44:47]
	v_mfma_f32_16x16x32_bf16 v[40:43], v[100:103], v[128:131], v[40:43]
	v_mfma_f32_16x16x32_bf16 v[28:31], v[108:111], v[104:107], v[28:31]
	v_mfma_f32_16x16x32_bf16 v[24:27], v[108:111], v[112:115], v[24:27]
	v_mfma_f32_16x16x32_bf16 v[12:15], v[108:111], v[120:123], v[12:15]
	v_mfma_f32_16x16x32_bf16 v[8:11], v[108:111], v[128:131], v[8:11]
	v_mfma_f32_16x16x32_bf16 v[48:51], v[116:119], v[104:107], v[48:51]
	v_mfma_f32_16x16x32_bf16 v[52:55], v[116:119], v[112:115], v[52:55]
	v_mfma_f32_16x16x32_bf16 v[32:35], v[116:119], v[120:123], v[32:35]
	v_mfma_f32_16x16x32_bf16 v[36:39], v[116:119], v[128:131], v[36:39]
	v_mfma_f32_16x16x32_bf16 v[16:19], v[124:127], v[104:107], v[16:19]
	v_mfma_f32_16x16x32_bf16 v[20:23], v[124:127], v[112:115], v[20:23]
	v_mfma_f32_16x16x32_bf16 v[0:3], v[124:127], v[120:123], v[0:3]
	v_mfma_f32_16x16x32_bf16 v[4:7], v[124:127], v[128:131], v[4:7]
	global_load_dwordx4 v[100:103], v[172:173], off offset:512
	global_load_dwordx4 v[104:107], v[174:175], off offset:512
	global_load_dwordx4 v[108:111], v[186:187], off offset:512
	global_load_dwordx4 v[112:115], v[188:189], off offset:512
	global_load_dwordx4 v[116:119], v[202:203], off offset:512
	global_load_dwordx4 v[120:123], v[228:229], off offset:512
	global_load_dwordx4 v[124:127], v[234:235], off offset:512
	global_load_dwordx4 v[128:131], v[82:83], off offset:512
	s_waitcnt vmcnt(24)
	v_mfma_f32_16x16x32_bf16 v[60:63], v[132:135], v[136:139], v[60:63]
	v_mfma_f32_16x16x32_bf16 v[56:59], v[132:135], v[144:147], v[56:59]
	v_mfma_f32_16x16x32_bf16 v[44:47], v[132:135], v[152:155], v[44:47]
	v_mfma_f32_16x16x32_bf16 v[40:43], v[132:135], v[160:163], v[40:43]
	v_mfma_f32_16x16x32_bf16 v[28:31], v[140:143], v[136:139], v[28:31]
	v_mfma_f32_16x16x32_bf16 v[24:27], v[140:143], v[144:147], v[24:27]
	v_mfma_f32_16x16x32_bf16 v[12:15], v[140:143], v[152:155], v[12:15]
	v_mfma_f32_16x16x32_bf16 v[8:11], v[140:143], v[160:163], v[8:11]
	v_mfma_f32_16x16x32_bf16 v[48:51], v[148:151], v[136:139], v[48:51]
	v_mfma_f32_16x16x32_bf16 v[52:55], v[148:151], v[144:147], v[52:55]
	v_mfma_f32_16x16x32_bf16 v[32:35], v[148:151], v[152:155], v[32:35]
	v_mfma_f32_16x16x32_bf16 v[36:39], v[148:151], v[160:163], v[36:39]
	v_mfma_f32_16x16x32_bf16 v[16:19], v[156:159], v[136:139], v[16:19]
	v_mfma_f32_16x16x32_bf16 v[20:23], v[156:159], v[144:147], v[20:23]
	v_mfma_f32_16x16x32_bf16 v[0:3], v[156:159], v[152:155], v[0:3]
	v_mfma_f32_16x16x32_bf16 v[4:7], v[156:159], v[160:163], v[4:7]
	global_load_dwordx4 v[132:135], v[172:173], off offset:1024
	global_load_dwordx4 v[136:139], v[174:175], off offset:1024
	global_load_dwordx4 v[140:143], v[186:187], off offset:1024
	global_load_dwordx4 v[144:147], v[188:189], off offset:1024
	global_load_dwordx4 v[148:151], v[202:203], off offset:1024
	global_load_dwordx4 v[152:155], v[228:229], off offset:1024
	global_load_dwordx4 v[156:159], v[234:235], off offset:1024
	global_load_dwordx4 v[160:163], v[82:83], off offset:1024
	s_waitcnt vmcnt(24)
	v_mfma_f32_16x16x32_bf16 v[60:63], v[204:207], v[208:211], v[60:63]
	v_mfma_f32_16x16x32_bf16 v[56:59], v[204:207], v[224:227], v[56:59]
	v_mfma_f32_16x16x32_bf16 v[44:47], v[204:207], v[240:243], v[44:47]
	v_mfma_f32_16x16x32_bf16 v[40:43], v[204:207], v[248:251], v[40:43]
	v_mfma_f32_16x16x32_bf16 v[28:31], v[212:215], v[208:211], v[28:31]
	v_mfma_f32_16x16x32_bf16 v[24:27], v[212:215], v[224:227], v[24:27]
	v_mfma_f32_16x16x32_bf16 v[12:15], v[212:215], v[240:243], v[12:15]
	v_mfma_f32_16x16x32_bf16 v[8:11], v[212:215], v[248:251], v[8:11]
	v_mfma_f32_16x16x32_bf16 v[48:51], v[236:239], v[208:211], v[48:51]
	v_mfma_f32_16x16x32_bf16 v[52:55], v[236:239], v[224:227], v[52:55]
	v_mfma_f32_16x16x32_bf16 v[32:35], v[236:239], v[240:243], v[32:35]
	v_mfma_f32_16x16x32_bf16 v[36:39], v[236:239], v[248:251], v[36:39]
	v_mfma_f32_16x16x32_bf16 v[16:19], v[244:247], v[208:211], v[16:19]
	v_mfma_f32_16x16x32_bf16 v[20:23], v[244:247], v[224:227], v[20:23]
	v_mfma_f32_16x16x32_bf16 v[0:3], v[244:247], v[240:243], v[0:3]
	v_mfma_f32_16x16x32_bf16 v[4:7], v[244:247], v[248:251], v[4:7]
	s_waitcnt vmcnt(16)
; __device__ __forceinline__ float bflo(unsigned w) { return __uint_as_float(w << 16); }
; __device__ __forceinline__ float bfhi(unsigned w) { return __uint_as_float(w & 0xffff0000u); }
; #define TG_LOAD(A_, B_, KS_) do { const int ks_ = (KS_) < nks ? (KS_) : w; _Pragma("unroll") for (int i = 0; i < 4; ++i) { A_[i] = *(const bf16x8*)(ap + (size_t)i * 16 * K + ks_ * 32); B_[i] = *(const bf16x8*)(bp + (size_t)i * 16 * K + ks_ * 32); } } while (0)
; #define TG_MMA(A_, B_) do { _Pragma("unroll") for (int i = 0; i < 4; ++i) _Pragma("unroll") for (int j = 0; j < 4; ++j) acc[i][j] = __builtin_amdgcn_mfma_f32_16x16x32_bf16(A_[i], B_[j], acc[i][j], 0, 0, 0); } while (0)
; template <int EPI> __device__ __forceinline__ void tail_gemm(LAS unsigned char* lds, const bf16* Am, const bf16* Bt, int K, const TailEpi& E, int tid_in) {
;     ...
;         for (int ks = w; ks < nks; ks += 24) {
;             TG_LOAD(a2, b2, ks + 16); TG_MMA(a0, b0);
;             if (ks + 8 < nks) { TG_LOAD(a0, b0, ks + 24); TG_MMA(a1, b1); }
;             if (ks + 16 < nks) { TG_LOAD(a1, b1, ks + 32); TG_MMA(a2, b2); }
;         }
;     ...
;     } else {
;         const u32x4 zw = *(const u32x4*)(E.ZB + off);
;         f32x4 x0 = {bflo(zw.x), bfhi(zw.x), bflo(zw.y), bfhi(zw.y)}, x1 = {bflo(zw.z), bfhi(zw.z), bflo(zw.w), bfhi(zw.w)};
;         if (E.pst) {
;             const f32x4* sp = (const f32x4*)(E.pst + (size_t)row * 32); float s = 0.f, q = 0.f;
; #pragma unroll
;             for (int i = 0; i < 8; ++i) { const f32x4 t = sp[i]; s += t[0] + t[2]; q += t[1] + t[3]; }
;             const float mu = s * (1.f / D), rstd = __builtin_amdgcn_rsqf(fmaxf(q * (1.f / D) - mu * mu, 0.f) + LN_EPS);
;             const f32x4 g0 = *(const f32x4*)(E.pg + col), g1 = *(const f32x4*)(E.pg + col + 4), b0 = *(const f32x4*)(E.pb + col), b1 = *(const f32x4*)(E.pb + col + 4);
	v_mfma_f32_16x16x32_bf16 v[60:63], v[64:67], v[68:71], v[60:63]
	v_mfma_f32_16x16x32_bf16 v[56:59], v[64:67], v[76:79], v[56:59]
	v_mfma_f32_16x16x32_bf16 v[44:47], v[64:67], v[88:91], v[44:47]
	v_mfma_f32_16x16x32_bf16 v[40:43], v[64:67], v[96:99], v[40:43]
	v_mfma_f32_16x16x32_bf16 v[28:31], v[72:75], v[68:71], v[28:31]
	v_mfma_f32_16x16x32_bf16 v[24:27], v[72:75], v[76:79], v[24:27]
	v_mfma_f32_16x16x32_bf16 v[12:15], v[72:75], v[88:91], v[12:15]
	v_mfma_f32_16x16x32_bf16 v[8:11], v[72:75], v[96:99], v[8:11]
	v_mfma_f32_16x16x32_bf16 v[48:51], v[84:87], v[68:71], v[48:51]
	v_mfma_f32_16x16x32_bf16 v[52:55], v[84:87], v[76:79], v[52:55]
	v_mfma_f32_16x16x32_bf16 v[32:35], v[84:87], v[88:91], v[32:35]
	v_mfma_f32_16x16x32_bf16 v[36:39], v[84:87], v[96:99], v[36:39]
	v_mfma_f32_16x16x32_bf16 v[16:19], v[92:95], v[68:71], v[16:19]
	v_mfma_f32_16x16x32_bf16 v[20:23], v[92:95], v[76:79], v[20:23]
	v_mfma_f32_16x16x32_bf16 v[0:3], v[92:95], v[88:91], v[0:3]
	v_mfma_f32_16x16x32_bf16 v[4:7], v[92:95], v[96:99], v[4:7]
	s_waitcnt vmcnt(8)
	v_mfma_f32_16x16x32_bf16 v[60:63], v[100:103], v[104:107], v[60:63]
	v_mfma_f32_16x16x32_bf16 v[56:59], v[100:103], v[112:115], v[56:59]
	v_mfma_f32_16x16x32_bf16 v[44:47], v[100:103], v[120:123], v[44:47]
	v_mfma_f32_16x16x32_bf16 v[40:43], v[100:103], v[128:131], v[40:43]
	v_mfma_f32_16x16x32_bf16 v[28:31], v[108:111], v[104:107], v[28:31]
	v_mfma_f32_16x16x32_bf16 v[24:27], v[108:111], v[112:115], v[24:27]
	v_mfma_f32_16x16x32_bf16 v[12:15], v[108:111], v[120:123], v[12:15]
	v_mfma_f32_16x16x32_bf16 v[8:11], v[108:111], v[128:131], v[8:11]
	v_mfma_f32_16x16x32_bf16 v[48:51], v[116:119], v[104:107], v[48:51]
	v_mfma_f32_16x16x32_bf16 v[52:55], v[116:119], v[112:115], v[52:55]
	v_mfma_f32_16x16x32_bf16 v[32:35], v[116:119], v[120:123], v[32:35]
	v_mfma_f32_16x16x32_bf16 v[36:39], v[116:119], v[128:131], v[36:39]
	v_mfma_f32_16x16x32_bf16 v[16:19], v[124:127], v[104:107], v[16:19]
	v_mfma_f32_16x16x32_bf16 v[20:23], v[124:127], v[112:115], v[20:23]
	v_mfma_f32_16x16x32_bf16 v[0:3], v[124:127], v[120:123], v[0:3]
	v_mfma_f32_16x16x32_bf16 v[4:7], v[124:127], v[128:131], v[4:7]
	v_add_u32_e32 v172, s1, v178
	v_mov_b32_e32 v173, 0
	v_or_b32_e32 v174, s0, v179
	v_lshlrev_b64 v[186:187], 11, v[172:173]
	v_lshlrev_b32_e32 v188, 1, v174
	v_mov_b32_e32 v189, 0
	v_lshl_add_u64 v[186:187], v[186:187], 0, v[188:189]
	v_lshl_add_u64 v[202:203], s[20:21], 0, v[186:187]
	global_load_dwordx4 v[64:67], v[202:203], off
	v_lshlrev_b32_e32 v234, 2, v174
	global_load_dwordx4 v[104:107], v234, s[48:49] offset:16
	global_load_dwordx4 v[108:111], v234, s[48:49]
	global_load_dwordx4 v[112:115], v234, s[50:51] offset:16
	global_load_dwordx4 v[116:119], v234, s[50:51]
	v_lshlrev_b64 v[228:229], 7, v[172:173]
	v_lshl_add_u64 v[228:229], s[44:45], 0, v[228:229]
	global_load_dwordx4 v[68:71], v[228:229], off offset:48
	global_load_dwordx4 v[72:75], v[228:229], off offset:32
	global_load_dwordx4 v[76:79], v[228:229], off offset:16
	global_load_dwordx4 v[84:87], v[228:229], off
	global_load_dwordx4 v[88:91], v[228:229], off offset:112
	global_load_dwordx4 v[92:95], v[228:229], off offset:96
	global_load_dwordx4 v[96:99], v[228:229], off offset:80
	global_load_dwordx4 v[100:103], v[228:229], off offset:64
	s_waitcnt vmcnt(13)
.Ltl3_w:
	v_mfma_f32_16x16x32_bf16 v[60:63], v[132:135], v[136:139], v[60:63]
	v_mfma_f32_16x16x32_bf16 v[56:59], v[132:135], v[144:147], v[56:59]
	v_mfma_f32_16x16x32_bf16 v[44:47], v[132:135], v[152:155], v[44:47]
	v_mfma_f32_16x16x32_bf16 v[40:43], v[132:135], v[160:163], v[40:43]
	v_mfma_f32_16x16x32_bf16 v[28:31], v[140:143], v[136:139], v[28:31]
	v_mfma_f32_16x16x32_bf16 v[24:27], v[140:143], v[144:147], v[24:27]
	v_mfma_f32_16x16x32_bf16 v[12:15], v[140:143], v[152:155], v[12:15]
	v_mfma_f32_16x16x32_bf16 v[8:11], v[140:143], v[160:163], v[8:11]
	v_mfma_f32_16x16x32_bf16 v[48:51], v[148:151], v[136:139], v[48:51]
	v_mfma_f32_16x16x32_bf16 v[52:55], v[148:151], v[144:147], v[52:55]
	v_mfma_f32_16x16x32_bf16 v[32:35], v[148:151], v[152:155], v[32:35]
	v_mfma_f32_16x16x32_bf16 v[36:39], v[148:151], v[160:163], v[36:39]
	v_mfma_f32_16x16x32_bf16 v[16:19], v[156:159], v[136:139], v[16:19]
	v_mfma_f32_16x16x32_bf16 v[20:23], v[156:159], v[144:147], v[20:23]
	v_mfma_f32_16x16x32_bf16 v[0:3], v[156:159], v[152:155], v[0:3]
	v_mfma_f32_16x16x32_bf16 v[4:7], v[156:159], v[160:163], v[4:7]
	v_mov_b32_e32 v225, v80
	v_mov_b32_e32 v82, v81
	v_mov_b32_e32 v83, v81
; #define LAS __attribute__((address_space(3)))
; #define BAR_LDS() do { asm volatile("s_waitcnt lgkmcnt(0)" ::: "memory"); __builtin_amdgcn_s_barrier(); asm volatile("" ::: "memory"); } while (0)
; template <int EPI> __device__ __forceinline__ void tail_gemm(LAS unsigned char* lds, const bf16* Am, const bf16* Bt, int K, const TailEpi& E, int tid_in) {
;     ...
;     LAS float* part = (LAS float*)lds + (size_t)w * 64 * 65;
; #pragma unroll
;     for (int i = 0; i < 4; ++i)
; #pragma unroll
;         for (int j = 0; j < 4; ++j)
; #pragma unroll
;             for (int r = 0; r < 4; ++r) part[(16 * i + 4 * q4 + r) * 65 + 16 * j + l15] = acc[i][j][r];
;     BAR_LDS();
;     const int rl = tid >> 3, c8 = (tid & 7) * 8, row = row0 + rl, col = col0 + c8;
;     f32x4 v0 = {0.f, 0.f, 0.f, 0.f}, v1 = v0;
; #pragma unroll
;     for (int ww = 0; ww < 8; ++ww) { const LAS float* p = (const LAS float*)lds + (size_t)ww * 64 * 65 + rl * 65 + c8;
;         v0[0] += p[0]; v0[1] += p[1]; v0[2] += p[2]; v0[3] += p[3]; v1[0] += p[4]; v1[1] += p[5]; v1[2] += p[6]; v1[3] += p[7]; }
.LBB0_1761:
	s_or_b64 exec, exec, s[2:3]
	ds_write2_b32 v181, v60, v56 offset1:16
	ds_write2_b32 v181, v61, v57 offset0:65 offset1:81
	ds_write2_b32 v181, v62, v58 offset0:130 offset1:146
	ds_write2_b32 v181, v63, v59 offset0:195 offset1:211
	ds_write2_b32 v181, v44, v40 offset0:32 offset1:48
	ds_write2_b32 v181, v45, v41 offset0:97 offset1:113
	ds_write2_b32 v181, v46, v42 offset0:162 offset1:178
	ds_write2_b32 v181, v47, v43 offset0:227 offset1:243
	v_add_u32_e32 v40, 0x1000, v181
	ds_write2_b32 v40, v28, v24 offset0:16 offset1:32
	ds_write2_b32 v40, v29, v25 offset0:81 offset1:97
	ds_write2_b32 v40, v30, v26 offset0:146 offset1:162
	ds_write2_b32 v40, v31, v27 offset0:211 offset1:227
	ds_write2_b32 v40, v12, v8 offset0:48 offset1:64
	ds_write2_b32 v40, v13, v9 offset0:113 offset1:129
	ds_write2_b32 v40, v14, v10 offset0:178 offset1:194
	v_add_u32_e32 v8, 0x1200, v181
	ds_write2_b32 v8, v15, v11 offset0:115 offset1:131
	v_add_u32_e32 v8, 0x2000, v181
	ds_write2_b32 v8, v48, v52 offset0:32 offset1:48
	ds_write2_b32 v8, v49, v53 offset0:97 offset1:113
	ds_write2_b32 v8, v50, v54 offset0:162 offset1:178
	ds_write2_b32 v8, v51, v55 offset0:227 offset1:243
	ds_write2_b32 v8, v32, v36 offset0:64 offset1:80
	ds_write2_b32 v8, v33, v37 offset0:129 offset1:145
	ds_write2_b32 v8, v34, v38 offset0:194 offset1:210
	v_add_u32_e32 v8, 0x2400, v181
	ds_write2_b32 v8, v35, v39 offset0:3 offset1:19
	v_add_u32_e32 v8, 0x3000, v181
	v_add_u32_e32 v9, 0x3200, v181
	ds_write2_b32 v8, v16, v20 offset0:48 offset1:64
	ds_write2_b32 v8, v17, v21 offset0:113 offset1:129
	ds_write2_b32 v8, v18, v22 offset0:178 offset1:194
	ds_write2_b32 v9, v19, v23 offset0:115 offset1:131
	ds_write2_b32 v8, v0, v4 offset0:80 offset1:96
	ds_write2_b32 v8, v1, v5 offset0:145 offset1:161
	ds_write2_b32 v8, v2, v6 offset0:210 offset1:226
	v_add_u32_e32 v0, 0x3400, v181
	ds_write2_b32 v0, v3, v7 offset0:19 offset1:35
	s_waitcnt lgkmcnt(0)
	s_barrier
	v_add_u32_e32 v1, 0x4100, v180
	ds_read2_b32 v[2:3], v180 offset1:1
	ds_read2_b32 v[4:5], v1 offset1:1
	v_add_u32_e32 v1, 0x8200, v180
	ds_read2_b32 v[6:7], v1 offset1:1
	v_add_u32_e32 v1, 0xc300, v180
	ds_read2_b32 v[8:9], v1 offset1:1
	ds_read2_b32 v[10:11], v182 offset1:1
	ds_read2_b32 v[12:13], v190 offset1:1
	ds_read2_b32 v[14:15], v194 offset1:1
	ds_read2_b32 v[16:17], v198 offset1:1
	ds_read2_b32 v[18:19], v180 offset0:2 offset1:3
	v_add_u32_e32 v1, 0x4108, v180
	ds_read2_b32 v[20:21], v1 offset1:1
	v_add_u32_e32 v1, 0x8208, v180
	ds_read2_b32 v[22:23], v1 offset1:1
	s_waitcnt lgkmcnt(2)
	v_pk_add_f32 v[18:19], v[18:19], 0 op_sel_hi:[1,0]
	v_pk_add_f32 v[2:3], v[2:3], 0 op_sel_hi:[1,0]
	v_add_u32_e32 v1, 0xc308, v180
	v_pk_add_f32 v[2:3], v[2:3], v[4:5]
	s_waitcnt lgkmcnt(1)
	v_pk_add_f32 v[4:5], v[18:19], v[20:21]
	ds_read2_b32 v[24:25], v1 offset1:1
	ds_read2_b32 v[26:27], v183 offset1:1
	ds_read2_b32 v[28:29], v191 offset1:1
	ds_read2_b32 v[30:31], v195 offset1:1
	ds_read2_b32 v[32:33], v199 offset1:1
	s_waitcnt lgkmcnt(5)
	v_pk_add_f32 v[4:5], v[4:5], v[22:23]
	v_pk_add_f32 v[2:3], v[2:3], v[6:7]
	s_waitcnt lgkmcnt(4)
	v_pk_add_f32 v[4:5], v[4:5], v[24:25]
	v_pk_add_f32 v[2:3], v[2:3], v[8:9]
	s_waitcnt lgkmcnt(3)
	v_pk_add_f32 v[4:5], v[4:5], v[26:27]
	v_pk_add_f32 v[2:3], v[2:3], v[10:11]
	s_waitcnt lgkmcnt(2)
	v_pk_add_f32 v[4:5], v[4:5], v[28:29]
	v_pk_add_f32 v[2:3], v[2:3], v[12:13]
	s_waitcnt lgkmcnt(1)
	v_pk_add_f32 v[4:5], v[4:5], v[30:31]
	v_pk_add_f32 v[2:3], v[2:3], v[14:15]
	v_add_u32_e32 v1, 0x4110, v180
	v_pk_add_f32 v[16:17], v[2:3], v[16:17]
	s_waitcnt lgkmcnt(0)
	v_pk_add_f32 v[18:19], v[4:5], v[32:33]
	ds_read2_b32 v[2:3], v180 offset0:4 offset1:5
	ds_read2_b32 v[4:5], v1 offset1:1
	v_add_u32_e32 v1, 0x8210, v180
	ds_read2_b32 v[6:7], v1 offset1:1
	v_add_u32_e32 v1, 0xc310, v180
	ds_read2_b32 v[8:9], v1 offset1:1
	ds_read2_b32 v[10:11], v184 offset1:1
	ds_read2_b32 v[12:13], v192 offset1:1
	ds_read2_b32 v[14:15], v196 offset1:1
	ds_read2_b32 v[20:21], v200 offset1:1
	ds_read2_b32 v[22:23], v180 offset0:6 offset1:7
	v_add_u32_e32 v1, 0x4118, v180
	ds_read2_b32 v[24:25], v1 offset1:1
	v_add_u32_e32 v1, 0x8218, v180
	ds_read2_b32 v[26:27], v1 offset1:1
	s_waitcnt lgkmcnt(2)
	v_pk_add_f32 v[22:23], v[22:23], 0 op_sel_hi:[1,0]
	v_pk_add_f32 v[2:3], v[2:3], 0 op_sel_hi:[1,0]
	v_add_u32_e32 v1, 0xc318, v180
	v_pk_add_f32 v[2:3], v[2:3], v[4:5]
	s_waitcnt lgkmcnt(1)
	v_pk_add_f32 v[4:5], v[22:23], v[24:25]
	v_add_u32_e32 v0, s1, v178
	ds_read2_b32 v[28:29], v1 offset1:1
	ds_read2_b32 v[30:31], v185 offset1:1
	ds_read2_b32 v[32:33], v193 offset1:1
	ds_read2_b32 v[34:35], v197 offset1:1
	ds_read2_b32 v[36:37], v201 offset1:1
	s_waitcnt lgkmcnt(5)
	v_pk_add_f32 v[4:5], v[4:5], v[26:27]
	v_pk_add_f32 v[2:3], v[2:3], v[6:7]
	s_waitcnt lgkmcnt(4)
; __device__ __forceinline__ float bflo(unsigned w) { return __uint_as_float(w << 16); }
; __device__ __forceinline__ float bfhi(unsigned w) { return __uint_as_float(w & 0xffff0000u); }
; template <int EPI> __device__ __forceinline__ void tail_gemm(LAS unsigned char* lds, const bf16* Am, const bf16* Bt, int K, const TailEpi& E, int tid_in) {
;     ...
;     } else {
;         const u32x4 zw = *(const u32x4*)(E.ZB + off);
;         f32x4 x0 = {bflo(zw.x), bfhi(zw.x), bflo(zw.y), bfhi(zw.y)}, x1 = {bflo(zw.z), bfhi(zw.z), bflo(zw.w), bfhi(zw.w)};
;         if (E.pst) {
;             const f32x4* sp = (const f32x4*)(E.pst + (size_t)row * 32); float s = 0.f, q = 0.f;
; #pragma unroll
;             for (int i = 0; i < 8; ++i) { const f32x4 t = sp[i]; s += t[0] + t[2]; q += t[1] + t[3]; }
;             const float mu = s * (1.f / D), rstd = __builtin_amdgcn_rsqf(fmaxf(q * (1.f / D) - mu * mu, 0.f) + LN_EPS);
;             const f32x4 g0 = *(const f32x4*)(E.pg + col), g1 = *(const f32x4*)(E.pg + col + 4), b0 = *(const f32x4*)(E.pb + col), b1 = *(const f32x4*)(E.pb + col + 4);
;             x0 = (x0 - mu) * rstd * g0 + b0; x1 = (x1 - mu) * rstd * g1 + b1;
;         }
;         x0 = x0 * ALPHA + v0; x1 = x1 * ALPHA + v1;
;         if (E.Z) { *(f32x4*)(E.Z + off) = x0; *(f32x4*)(E.Z + off + 4) = x1; }
	v_pk_add_f32 v[4:5], v[4:5], v[28:29]
	v_pk_add_f32 v[2:3], v[2:3], v[8:9]
	v_ashrrev_i32_e32 v1, 31, v0
	s_waitcnt lgkmcnt(3)
	v_pk_add_f32 v[4:5], v[4:5], v[30:31]
	v_pk_add_f32 v[2:3], v[2:3], v[10:11]
	v_or_b32_e32 v41, s0, v179
	v_lshlrev_b64 v[28:29], 10, v[0:1]
	v_pk_add_f32 v[2:3], v[2:3], v[12:13]
	s_waitcnt lgkmcnt(2)
	v_pk_add_f32 v[4:5], v[4:5], v[32:33]
	v_or_b32_e32 v28, v28, v41
	s_waitcnt lgkmcnt(1)
	v_pk_add_f32 v[4:5], v[4:5], v[34:35]
	v_pk_add_f32 v[2:3], v[2:3], v[14:15]
	v_lshl_add_u64 v[26:27], v[28:29], 1, s[20:21]
	v_pk_add_f32 v[20:21], v[2:3], v[20:21]
	s_waitcnt lgkmcnt(0)
	v_pk_add_f32 v[22:23], v[4:5], v[36:37]
	s_waitcnt vmcnt(0)
	v_mov_b32_e32 v2, v64
	v_mov_b32_e32 v3, v65
	v_mov_b32_e32 v4, v66
	v_mov_b32_e32 v5, v67
	v_lshlrev_b64 v[24:25], 7, v[0:1]
	v_lshl_add_u64 v[32:33], s[44:45], 0, v[24:25]
	s_mov_b32 s0, 0x3a800000
	s_and_b64 vcc, exec, s[46:47]
	s_waitcnt vmcnt(0)
	v_lshlrev_b32_e32 v37, 16, v2
	v_and_b32_e32 v39, 0xffff0000, v2
	v_lshlrev_b32_e32 v38, 16, v3
	v_and_b32_e32 v40, 0xffff0000, v3
	v_lshlrev_b32_e32 v31, 16, v4
	v_and_b32_e32 v35, 0xffff0000, v4
	v_lshlrev_b32_e32 v34, 16, v5
	v_and_b32_e32 v36, 0xffff0000, v5
	s_waitcnt vmcnt(0)
	v_mov_b32_e32 v0, v68
	v_mov_b32_e32 v1, v69
	v_mov_b32_e32 v2, v70
	v_mov_b32_e32 v3, v71
	s_waitcnt vmcnt(0)
	v_mov_b32_e32 v4, v72
	v_mov_b32_e32 v5, v73
	v_mov_b32_e32 v6, v74
	v_mov_b32_e32 v7, v75
	s_waitcnt vmcnt(0)
	v_mov_b32_e32 v8, v76
	v_mov_b32_e32 v9, v77
	v_mov_b32_e32 v10, v78
	v_mov_b32_e32 v11, v79
	s_waitcnt vmcnt(0)
	v_mov_b32_e32 v12, v84
	v_mov_b32_e32 v13, v85
	v_mov_b32_e32 v14, v86
	v_mov_b32_e32 v15, v87
	s_waitcnt vmcnt(0)
	v_mov_b32_e32 v42, v88
	v_mov_b32_e32 v43, v89
	v_mov_b32_e32 v44, v90
	v_mov_b32_e32 v45, v91
	s_waitcnt vmcnt(0)
	v_mov_b32_e32 v46, v92
	v_mov_b32_e32 v47, v93
	v_mov_b32_e32 v48, v94
	v_mov_b32_e32 v49, v95
	s_waitcnt vmcnt(0)
	v_mov_b32_e32 v50, v96
	v_mov_b32_e32 v51, v97
	v_mov_b32_e32 v52, v98
	v_mov_b32_e32 v53, v99
	s_waitcnt vmcnt(0)
	v_mov_b32_e32 v54, v100
	v_mov_b32_e32 v55, v101
	v_mov_b32_e32 v56, v102
	v_mov_b32_e32 v57, v103
	s_waitcnt vmcnt(7)
	v_pk_add_f32 v[0:1], v[0:1], v[2:3]
	s_waitcnt vmcnt(6)
	v_pk_add_f32 v[4:5], v[4:5], v[6:7]
	s_waitcnt vmcnt(5)
	v_pk_add_f32 v[8:9], v[8:9], v[10:11]
	s_waitcnt vmcnt(4)
	v_pk_add_f32 v[12:13], v[12:13], v[14:15]
	s_waitcnt vmcnt(0)
	v_pk_add_f32 v[2:3], v[54:55], v[56:57]
	v_pk_add_f32 v[12:13], v[12:13], 0 op_sel_hi:[1,0]
	s_nop 0
	v_pk_add_f32 v[8:9], v[12:13], v[8:9]
	v_lshlrev_b32_e32 v12, 2, v41
	v_pk_add_f32 v[4:5], v[8:9], v[4:5]
	s_nop 0
	v_pk_add_f32 v[0:1], v[4:5], v[0:1]
	s_nop 0
	v_pk_add_f32 v[0:1], v[0:1], v[2:3]
	v_pk_add_f32 v[2:3], v[50:51], v[52:53]
	s_nop 0
	v_pk_add_f32 v[0:1], v[0:1], v[2:3]
	v_pk_add_f32 v[2:3], v[46:47], v[48:49]
	s_nop 0
	v_pk_add_f32 v[0:1], v[0:1], v[2:3]
	v_pk_add_f32 v[2:3], v[42:43], v[44:45]
	s_nop 0
	v_pk_add_f32 v[0:1], v[0:1], v[2:3]
	s_nop 0
	v_pk_mul_f32 v[32:33], v[0:1], s[0:1] op_sel_hi:[1,0]
	s_nop 0
	v_fma_f32 v0, -v32, v32, v33
	v_max_f32_e32 v0, 0, v0
	v_add_f32_e32 v0, 0x3727c5ac, v0
	v_rsq_f32_e32 v30, v0
	s_waitcnt vmcnt(0)
	v_mov_b32_e32 v0, v104
	v_mov_b32_e32 v1, v105
	v_mov_b32_e32 v2, v106
	v_mov_b32_e32 v3, v107
	s_waitcnt vmcnt(0)
	v_mov_b32_e32 v8, v108
	v_mov_b32_e32 v9, v109
	v_mov_b32_e32 v10, v110
	v_mov_b32_e32 v11, v111
	s_waitcnt vmcnt(0)
	v_mov_b32_e32 v4, v112
	v_mov_b32_e32 v5, v113
	v_mov_b32_e32 v6, v114
	v_mov_b32_e32 v7, v115
	s_nop 0
	s_waitcnt vmcnt(0)
	v_mov_b32_e32 v12, v116
	v_mov_b32_e32 v13, v117
	v_mov_b32_e32 v14, v118
	v_mov_b32_e32 v15, v119
	v_sub_f32_e32 v43, v39, v32
	v_sub_f32_e32 v42, v37, v32
	v_sub_f32_e32 v39, v40, v32
	v_sub_f32_e32 v38, v38, v32
	v_pk_mul_f32 v[38:39], v[38:39], v[30:31] op_sel_hi:[1,0]
	v_pk_mul_f32 v[40:41], v[42:43], v[30:31] op_sel_hi:[1,0]
	s_waitcnt vmcnt(0)
	v_pk_fma_f32 v[10:11], v[10:11], v[38:39], v[14:15]
	v_pk_fma_f32 v[8:9], v[8:9], v[40:41], v[12:13]
	v_sub_f32_e32 v13, v35, v32
	v_sub_f32_e32 v12, v31, v32
	v_sub_f32_e32 v15, v36, v32
	v_sub_f32_e32 v14, v34, v32
	v_pk_mul_f32 v[14:15], v[14:15], v[30:31] op_sel_hi:[1,0]
	v_pk_mul_f32 v[12:13], v[12:13], v[30:31] op_sel_hi:[1,0]
	v_pk_fma_f32 v[2:3], v[2:3], v[14:15], v[6:7]
	v_pk_fma_f32 v[0:1], v[0:1], v[12:13], v[4:5]
	v_pk_fma_f32 v[6:7], v[10:11], s[34:35], v[18:19] op_sel_hi:[1,0,1]
	v_pk_fma_f32 v[4:5], v[8:9], s[34:35], v[16:17] op_sel_hi:[1,0,1]
	v_pk_fma_f32 v[2:3], v[2:3], s[34:35], v[22:23] op_sel_hi:[1,0,1]
	v_pk_fma_f32 v[0:1], v[0:1], s[34:35], v[20:21] op_sel_hi:[1,0,1]
	s_cbranch_vccz .LBB0_1763
	v_lshl_add_u64 v[8:9], v[28:29], 2, s[96:97]
	global_store_dwordx4 v[8:9], v[4:7], off
	global_store_dwordx4 v[8:9], v[0:3], off offset:16
